# GEMM K-loops: s_setprio roles swapped (load part prio 1, MFMA block prio 0)
# speedup vs baseline: 1.0151x; 1.0077x over previous
.Lwe_0:
	s_waitcnt lgkmcnt(0)
	s_barrier
	s_setprio 0
	s_waitcnt lgkmcnt(0)
	v_mfma_f32_16x16x32_bf16 v[126:129], v[158:161], v[190:193], v[126:129]
	v_mfma_f32_16x16x32_bf16 v[122:125], v[166:169], v[190:193], v[122:125]
	v_mfma_f32_16x16x32_bf16 v[118:121], v[158:161], v[198:201], v[118:121]
	v_mfma_f32_16x16x32_bf16 v[110:113], v[166:169], v[198:201], v[110:113]
	v_mfma_f32_16x16x32_bf16 v[102:105], v[158:161], v[206:209], v[102:105]
	v_mfma_f32_16x16x32_bf16 v[94:97], v[166:169], v[206:209], v[94:97]
	v_mfma_f32_16x16x32_bf16 v[86:89], v[158:161], v[214:217], v[86:89]
	v_mfma_f32_16x16x32_bf16 v[78:81], v[166:169], v[214:217], v[78:81]
	v_mfma_f32_16x16x32_bf16 v[126:129], v[162:165], v[194:197], v[126:129]
	v_mfma_f32_16x16x32_bf16 v[122:125], v[170:173], v[194:197], v[122:125]
	v_mfma_f32_16x16x32_bf16 v[118:121], v[162:165], v[202:205], v[118:121]
	v_mfma_f32_16x16x32_bf16 v[110:113], v[170:173], v[202:205], v[110:113]
	v_mfma_f32_16x16x32_bf16 v[102:105], v[162:165], v[210:213], v[102:105]
	v_mfma_f32_16x16x32_bf16 v[94:97], v[170:173], v[210:213], v[94:97]
	v_mfma_f32_16x16x32_bf16 v[86:89], v[162:165], v[218:221], v[86:89]
	v_mfma_f32_16x16x32_bf16 v[78:81], v[170:173], v[218:221], v[78:81]
	s_setprio 1
	s_setprio 0
	v_mfma_f32_16x16x32_bf16 v[114:117], v[174:177], v[190:193], v[114:117]
	v_mfma_f32_16x16x32_bf16 v[106:109], v[182:185], v[190:193], v[106:109]
	v_mfma_f32_16x16x32_bf16 v[98:101], v[174:177], v[198:201], v[98:101]
	v_mfma_f32_16x16x32_bf16 v[90:93], v[182:185], v[198:201], v[90:93]
	v_mfma_f32_16x16x32_bf16 v[82:85], v[174:177], v[206:209], v[82:85]
	v_mfma_f32_16x16x32_bf16 v[74:77], v[182:185], v[206:209], v[74:77]
	v_mfma_f32_16x16x32_bf16 v[70:73], v[174:177], v[214:217], v[70:73]
	v_mfma_f32_16x16x32_bf16 v[66:69], v[182:185], v[214:217], v[66:69]
	v_mfma_f32_16x16x32_bf16 v[114:117], v[178:181], v[194:197], v[114:117]
	v_mfma_f32_16x16x32_bf16 v[106:109], v[186:189], v[194:197], v[106:109]
	v_mfma_f32_16x16x32_bf16 v[98:101], v[178:181], v[202:205], v[98:101]
	v_mfma_f32_16x16x32_bf16 v[90:93], v[186:189], v[202:205], v[90:93]
	v_mfma_f32_16x16x32_bf16 v[82:85], v[178:181], v[210:213], v[82:85]
	v_mfma_f32_16x16x32_bf16 v[74:77], v[186:189], v[210:213], v[74:77]
	v_mfma_f32_16x16x32_bf16 v[70:73], v[178:181], v[218:221], v[70:73]
	v_mfma_f32_16x16x32_bf16 v[66:69], v[186:189], v[218:221], v[66:69]
	s_setprio 1
	s_barrier
	s_add_i32 s68, s58, s46
	v_lshl_add_u64 v[222:223], s[40:41], 0, v[134:135]
	s_mov_b32 m0, s68
	ds_read_b128 v[190:193], v156 offset:16384
	ds_read_b128 v[194:197], v156 offset:17408
	ds_read_b128 v[198:201], v156 offset:18432
	ds_read_b128 v[202:205], v156 offset:19456
	ds_read_b128 v[206:209], v156 offset:20480
	ds_read_b128 v[210:213], v156 offset:21504
	ds_read_b128 v[214:217], v156 offset:22528
	ds_read_b128 v[218:221], v156 offset:23552
	global_load_lds_dwordx4 v[222:223], off
	s_add_i32 m0, s68, 0x2000
	s_add_u32 s68, s40, 0x80000
	v_lshl_add_u64 v[224:225], s[40:41], 0, v[130:131]
	s_addc_u32 s69, s41, 0
	s_add_i32 s71, s59, s46
	global_load_lds_dwordx4 v[224:225], off
	v_lshl_add_u64 v[226:227], s[68:69], 0, v[134:135]
	s_mov_b32 m0, s71
	v_lshl_add_u64 v[228:229], s[42:43], 0, v[132:133]
	global_load_lds_dwordx4 v[226:227], off
	v_lshl_add_u64 v[226:227], s[68:69], 0, v[130:131]
	s_add_i32 m0, s71, 0x2000
	s_nop 0
	global_load_lds_dwordx4 v[226:227], off
	v_lshl_add_u64 v[226:227], s[42:43], 0, v[136:137]
	s_mov_b32 m0, s49
	s_nop 0
	global_load_lds_dwordx4 v[226:227], off
	s_mov_b32 m0, s50
	s_nop 0
	global_load_lds_dwordx4 v[228:229], off
	s_cmp_eq_u32 s70, 0
	s_cbranch_scc1 .Lw8_1
	s_waitcnt vmcnt(24)
	s_branch .Lwe_1

.Lwe_1:
	s_waitcnt lgkmcnt(0)
	s_barrier
	s_setprio 0
	s_waitcnt lgkmcnt(0)
	v_mfma_f32_16x16x32_bf16 v[62:65], v[158:161], v[190:193], v[62:65]
	v_mfma_f32_16x16x32_bf16 v[58:61], v[166:169], v[190:193], v[58:61]
	v_mfma_f32_16x16x32_bf16 v[54:57], v[158:161], v[198:201], v[54:57]
	v_mfma_f32_16x16x32_bf16 v[46:49], v[166:169], v[198:201], v[46:49]
	v_mfma_f32_16x16x32_bf16 v[38:41], v[158:161], v[206:209], v[38:41]
	v_mfma_f32_16x16x32_bf16 v[30:33], v[166:169], v[206:209], v[30:33]
	v_mfma_f32_16x16x32_bf16 v[22:25], v[158:161], v[214:217], v[22:25]
	v_mfma_f32_16x16x32_bf16 v[14:17], v[166:169], v[214:217], v[14:17]
	v_mfma_f32_16x16x32_bf16 v[62:65], v[162:165], v[194:197], v[62:65]
	v_mfma_f32_16x16x32_bf16 v[58:61], v[170:173], v[194:197], v[58:61]
	v_mfma_f32_16x16x32_bf16 v[54:57], v[162:165], v[202:205], v[54:57]
	v_mfma_f32_16x16x32_bf16 v[46:49], v[170:173], v[202:205], v[46:49]
	v_mfma_f32_16x16x32_bf16 v[38:41], v[162:165], v[210:213], v[38:41]
	v_mfma_f32_16x16x32_bf16 v[30:33], v[170:173], v[210:213], v[30:33]
	v_mfma_f32_16x16x32_bf16 v[22:25], v[162:165], v[218:221], v[22:25]
	v_mfma_f32_16x16x32_bf16 v[14:17], v[170:173], v[218:221], v[14:17]
	s_setprio 1
	s_setprio 0
	v_mfma_f32_16x16x32_bf16 v[50:53], v[174:177], v[190:193], v[50:53]
	v_mfma_f32_16x16x32_bf16 v[42:45], v[182:185], v[190:193], v[42:45]
	v_mfma_f32_16x16x32_bf16 v[34:37], v[174:177], v[198:201], v[34:37]
	v_mfma_f32_16x16x32_bf16 v[26:29], v[182:185], v[198:201], v[26:29]
	v_mfma_f32_16x16x32_bf16 v[18:21], v[174:177], v[206:209], v[18:21]
	v_mfma_f32_16x16x32_bf16 v[10:13], v[182:185], v[206:209], v[10:13]
	v_mfma_f32_16x16x32_bf16 v[6:9], v[174:177], v[214:217], v[6:9]
	v_mfma_f32_16x16x32_bf16 v[2:5], v[182:185], v[214:217], v[2:5]
	v_mfma_f32_16x16x32_bf16 v[50:53], v[178:181], v[194:197], v[50:53]
	v_mfma_f32_16x16x32_bf16 v[42:45], v[186:189], v[194:197], v[42:45]
	v_mfma_f32_16x16x32_bf16 v[34:37], v[178:181], v[202:205], v[34:37]
	v_mfma_f32_16x16x32_bf16 v[26:29], v[186:189], v[202:205], v[26:29]
	v_mfma_f32_16x16x32_bf16 v[18:21], v[178:181], v[210:213], v[18:21]
	v_mfma_f32_16x16x32_bf16 v[10:13], v[186:189], v[210:213], v[10:13]
	v_mfma_f32_16x16x32_bf16 v[6:9], v[178:181], v[218:221], v[6:9]
	v_mfma_f32_16x16x32_bf16 v[2:5], v[186:189], v[218:221], v[2:5]
	s_setprio 1
	s_barrier
	s_add_i32 s68, 0, 0x18000
	v_add_u32_e32 v157, s68, v150
	s_add_i32 s69, 0, 0x1c000
	ds_read_b128 v[158:161], v157
	ds_read_b128 v[162:165], v157 offset:1024
	ds_read_b128 v[166:169], v157 offset:2048
	ds_read_b128 v[170:173], v157 offset:3072
	v_add_u32_e32 v157, s69, v150
	ds_read_b128 v[174:177], v157
	ds_read_b128 v[178:181], v157 offset:1024
	ds_read_b128 v[182:185], v157 offset:2048
	ds_read_b128 v[186:189], v157 offset:3072
	s_add_u32 s42, s42, 0x80000
	s_addc_u32 s43, s43, 0
	s_mov_b32 m0, s51
	v_lshl_add_u64 v[230:231], s[42:43], 0, v[136:137]
	ds_read_b128 v[190:193], v156 offset:32768
	ds_read_b128 v[194:197], v156 offset:33792
	ds_read_b128 v[198:201], v156 offset:34816
	ds_read_b128 v[202:205], v156 offset:35840
	ds_read_b128 v[206:209], v156 offset:36864
	ds_read_b128 v[210:213], v156 offset:37888
	ds_read_b128 v[214:217], v156 offset:38912
	ds_read_b128 v[218:221], v156 offset:39936
	global_load_lds_dwordx4 v[230:231], off
	v_lshl_add_u64 v[230:231], s[42:43], 0, v[132:133]
	s_mov_b32 m0, s52
	s_nop 0
	global_load_lds_dwordx4 v[230:231], off
	s_waitcnt vmcnt(8)
	s_waitcnt lgkmcnt(0)
	s_barrier
	s_setprio 0
	s_waitcnt lgkmcnt(0)
	v_mfma_f32_16x16x32_bf16 v[126:129], v[158:161], v[190:193], v[126:129]
	v_mfma_f32_16x16x32_bf16 v[122:125], v[166:169], v[190:193], v[122:125]
	v_mfma_f32_16x16x32_bf16 v[118:121], v[158:161], v[198:201], v[118:121]
	v_mfma_f32_16x16x32_bf16 v[110:113], v[166:169], v[198:201], v[110:113]
	v_mfma_f32_16x16x32_bf16 v[102:105], v[158:161], v[206:209], v[102:105]
	v_mfma_f32_16x16x32_bf16 v[94:97], v[166:169], v[206:209], v[94:97]
	v_mfma_f32_16x16x32_bf16 v[86:89], v[158:161], v[214:217], v[86:89]
	v_mfma_f32_16x16x32_bf16 v[78:81], v[166:169], v[214:217], v[78:81]
	v_mfma_f32_16x16x32_bf16 v[126:129], v[162:165], v[194:197], v[126:129]
	v_mfma_f32_16x16x32_bf16 v[122:125], v[170:173], v[194:197], v[122:125]
	v_mfma_f32_16x16x32_bf16 v[118:121], v[162:165], v[202:205], v[118:121]
	v_mfma_f32_16x16x32_bf16 v[110:113], v[170:173], v[202:205], v[110:113]
	v_mfma_f32_16x16x32_bf16 v[102:105], v[162:165], v[210:213], v[102:105]
	v_mfma_f32_16x16x32_bf16 v[94:97], v[170:173], v[210:213], v[94:97]
	v_mfma_f32_16x16x32_bf16 v[86:89], v[162:165], v[218:221], v[86:89]
	v_mfma_f32_16x16x32_bf16 v[78:81], v[170:173], v[218:221], v[78:81]
	s_setprio 1
	s_setprio 0
	v_mfma_f32_16x16x32_bf16 v[114:117], v[174:177], v[190:193], v[114:117]
	v_mfma_f32_16x16x32_bf16 v[106:109], v[182:185], v[190:193], v[106:109]
	v_mfma_f32_16x16x32_bf16 v[98:101], v[174:177], v[198:201], v[98:101]
	v_mfma_f32_16x16x32_bf16 v[90:93], v[182:185], v[198:201], v[90:93]
	v_mfma_f32_16x16x32_bf16 v[82:85], v[174:177], v[206:209], v[82:85]
	v_mfma_f32_16x16x32_bf16 v[74:77], v[182:185], v[206:209], v[74:77]
	v_mfma_f32_16x16x32_bf16 v[70:73], v[174:177], v[214:217], v[70:73]
	v_mfma_f32_16x16x32_bf16 v[66:69], v[182:185], v[214:217], v[66:69]
	v_mfma_f32_16x16x32_bf16 v[114:117], v[178:181], v[194:197], v[114:117]
	v_mfma_f32_16x16x32_bf16 v[106:109], v[186:189], v[194:197], v[106:109]
	v_mfma_f32_16x16x32_bf16 v[98:101], v[178:181], v[202:205], v[98:101]
	v_mfma_f32_16x16x32_bf16 v[90:93], v[186:189], v[202:205], v[90:93]
	v_mfma_f32_16x16x32_bf16 v[82:85], v[178:181], v[210:213], v[82:85]
	v_mfma_f32_16x16x32_bf16 v[74:77], v[186:189], v[210:213], v[74:77]
	v_mfma_f32_16x16x32_bf16 v[70:73], v[178:181], v[218:221], v[70:73]
	v_mfma_f32_16x16x32_bf16 v[66:69], v[186:189], v[218:221], v[66:69]
	s_setprio 1
	s_barrier
	s_add_i32 s42, s68, s46
	v_lshl_add_u64 v[222:223], v[222:223], 0, s[12:13]
	s_mov_b32 m0, s42
	ds_read_b128 v[190:193], v156 offset:49152
	ds_read_b128 v[194:197], v156 offset:50176
	ds_read_b128 v[198:201], v156 offset:51200
	ds_read_b128 v[202:205], v156 offset:52224
	ds_read_b128 v[206:209], v156 offset:53248
	ds_read_b128 v[210:213], v156 offset:54272
	ds_read_b128 v[214:217], v156 offset:55296
	ds_read_b128 v[218:221], v156 offset:56320
	global_load_lds_dwordx4 v[222:223], off
	s_add_i32 m0, s42, 0x2000
	s_add_u32 s40, s40, 0x80080
	v_lshl_add_u64 v[222:223], v[224:225], 0, s[12:13]
	s_addc_u32 s41, s41, 0
	s_add_i32 s42, s69, s46
	global_load_lds_dwordx4 v[222:223], off
	v_lshl_add_u64 v[222:223], s[40:41], 0, v[134:135]
	s_mov_b32 m0, s42
	s_nop 0
	global_load_lds_dwordx4 v[222:223], off
	v_lshl_add_u64 v[222:223], s[40:41], 0, v[130:131]
	s_add_i32 m0, s42, 0x2000
	s_nop 0
	global_load_lds_dwordx4 v[222:223], off
	v_lshl_add_u64 v[222:223], v[226:227], 0, s[12:13]
	s_mov_b32 m0, s54
	s_nop 0
	global_load_lds_dwordx4 v[222:223], off
	v_lshl_add_u64 v[222:223], v[228:229], 0, s[12:13]
	s_mov_b32 m0, s55
	s_nop 0
	global_load_lds_dwordx4 v[222:223], off
	s_waitcnt vmcnt(8)
	s_waitcnt lgkmcnt(0)
	s_barrier
	s_setprio 0
	s_waitcnt lgkmcnt(0)
	v_mfma_f32_16x16x32_bf16 v[62:65], v[158:161], v[190:193], v[62:65]
	v_mfma_f32_16x16x32_bf16 v[58:61], v[166:169], v[190:193], v[58:61]
	v_mfma_f32_16x16x32_bf16 v[54:57], v[158:161], v[198:201], v[54:57]
	v_mfma_f32_16x16x32_bf16 v[46:49], v[166:169], v[198:201], v[46:49]
	v_mfma_f32_16x16x32_bf16 v[38:41], v[158:161], v[206:209], v[38:41]
	v_mfma_f32_16x16x32_bf16 v[30:33], v[166:169], v[206:209], v[30:33]
	v_mfma_f32_16x16x32_bf16 v[22:25], v[158:161], v[214:217], v[22:25]
	v_mfma_f32_16x16x32_bf16 v[14:17], v[166:169], v[214:217], v[14:17]
	v_mfma_f32_16x16x32_bf16 v[62:65], v[162:165], v[194:197], v[62:65]
	v_mfma_f32_16x16x32_bf16 v[58:61], v[170:173], v[194:197], v[58:61]
	v_mfma_f32_16x16x32_bf16 v[54:57], v[162:165], v[202:205], v[54:57]
	v_mfma_f32_16x16x32_bf16 v[46:49], v[170:173], v[202:205], v[46:49]
	v_mfma_f32_16x16x32_bf16 v[38:41], v[162:165], v[210:213], v[38:41]
	v_mfma_f32_16x16x32_bf16 v[30:33], v[170:173], v[210:213], v[30:33]
	v_mfma_f32_16x16x32_bf16 v[22:25], v[162:165], v[218:221], v[22:25]
	v_mfma_f32_16x16x32_bf16 v[14:17], v[170:173], v[218:221], v[14:17]
	s_setprio 1
	s_setprio 0
	v_mfma_f32_16x16x32_bf16 v[50:53], v[174:177], v[190:193], v[50:53]
	v_mfma_f32_16x16x32_bf16 v[42:45], v[182:185], v[190:193], v[42:45]
	v_mfma_f32_16x16x32_bf16 v[34:37], v[174:177], v[198:201], v[34:37]
	v_mfma_f32_16x16x32_bf16 v[26:29], v[182:185], v[198:201], v[26:29]
	v_mfma_f32_16x16x32_bf16 v[18:21], v[174:177], v[206:209], v[18:21]
	v_mfma_f32_16x16x32_bf16 v[10:13], v[182:185], v[206:209], v[10:13]
	v_mfma_f32_16x16x32_bf16 v[6:9], v[174:177], v[214:217], v[6:9]
	v_mfma_f32_16x16x32_bf16 v[2:5], v[182:185], v[214:217], v[2:5]
	v_mfma_f32_16x16x32_bf16 v[50:53], v[178:181], v[194:197], v[50:53]
	v_mfma_f32_16x16x32_bf16 v[42:45], v[186:189], v[194:197], v[42:45]
	v_mfma_f32_16x16x32_bf16 v[34:37], v[178:181], v[202:205], v[34:37]
	v_mfma_f32_16x16x32_bf16 v[26:29], v[186:189], v[202:205], v[26:29]
	v_mfma_f32_16x16x32_bf16 v[18:21], v[178:181], v[210:213], v[18:21]
	v_mfma_f32_16x16x32_bf16 v[10:13], v[186:189], v[210:213], v[10:13]
	v_mfma_f32_16x16x32_bf16 v[6:9], v[178:181], v[218:221], v[6:9]
	v_mfma_f32_16x16x32_bf16 v[2:5], v[186:189], v[218:221], v[2:5]
	s_setprio 1
	s_barrier
	s_add_i32 s67, s67, 2
	s_add_u32 s38, s38, 0x100
	s_addc_u32 s39, s39, 0
	s_cmp_gt_u32 s67, 29
	s_cbranch_scc0 .LBB0_346
	s_and_b64 vcc, exec, s[14:15]
	s_cbranch_vccnz .LBB0_351
	s_mov_b64 s[30:31], -1
	s_and_b64 vcc, exec, s[34:35]
	s_cbranch_vccnz .LBB0_352

.Lwe_2:
	s_waitcnt lgkmcnt(0)
	s_barrier
	s_setprio 0
	s_waitcnt lgkmcnt(0)
	v_mfma_f32_16x16x32_bf16 v[126:129], v[158:161], v[190:193], v[126:129]
	v_mfma_f32_16x16x32_bf16 v[122:125], v[166:169], v[190:193], v[122:125]
	v_mfma_f32_16x16x32_bf16 v[110:113], v[158:161], v[198:201], v[110:113]
	v_mfma_f32_16x16x32_bf16 v[106:109], v[166:169], v[198:201], v[106:109]
	v_mfma_f32_16x16x32_bf16 v[94:97], v[158:161], v[206:209], v[94:97]
	v_mfma_f32_16x16x32_bf16 v[90:93], v[166:169], v[206:209], v[90:93]
	v_mfma_f32_16x16x32_bf16 v[78:81], v[158:161], v[214:217], v[78:81]
	v_mfma_f32_16x16x32_bf16 v[74:77], v[166:169], v[214:217], v[74:77]
	v_mfma_f32_16x16x32_bf16 v[126:129], v[162:165], v[194:197], v[126:129]
	v_mfma_f32_16x16x32_bf16 v[122:125], v[170:173], v[194:197], v[122:125]
	v_mfma_f32_16x16x32_bf16 v[110:113], v[162:165], v[202:205], v[110:113]
	v_mfma_f32_16x16x32_bf16 v[106:109], v[170:173], v[202:205], v[106:109]
	v_mfma_f32_16x16x32_bf16 v[94:97], v[162:165], v[210:213], v[94:97]
	v_mfma_f32_16x16x32_bf16 v[90:93], v[170:173], v[210:213], v[90:93]
	v_mfma_f32_16x16x32_bf16 v[78:81], v[162:165], v[218:221], v[78:81]
	v_mfma_f32_16x16x32_bf16 v[74:77], v[170:173], v[218:221], v[74:77]
	s_setprio 1
	s_setprio 0
	v_mfma_f32_16x16x32_bf16 v[118:121], v[174:177], v[190:193], v[118:121]
	v_mfma_f32_16x16x32_bf16 v[114:117], v[182:185], v[190:193], v[114:117]
	v_mfma_f32_16x16x32_bf16 v[102:105], v[174:177], v[198:201], v[102:105]
	v_mfma_f32_16x16x32_bf16 v[98:101], v[182:185], v[198:201], v[98:101]
	v_mfma_f32_16x16x32_bf16 v[86:89], v[174:177], v[206:209], v[86:89]
	v_mfma_f32_16x16x32_bf16 v[82:85], v[182:185], v[206:209], v[82:85]
	v_mfma_f32_16x16x32_bf16 v[70:73], v[174:177], v[214:217], v[70:73]
	v_mfma_f32_16x16x32_bf16 v[66:69], v[182:185], v[214:217], v[66:69]
	v_mfma_f32_16x16x32_bf16 v[118:121], v[178:181], v[194:197], v[118:121]
	v_mfma_f32_16x16x32_bf16 v[114:117], v[186:189], v[194:197], v[114:117]
	v_mfma_f32_16x16x32_bf16 v[102:105], v[178:181], v[202:205], v[102:105]
	v_mfma_f32_16x16x32_bf16 v[98:101], v[186:189], v[202:205], v[98:101]
	v_mfma_f32_16x16x32_bf16 v[86:89], v[178:181], v[210:213], v[86:89]
	v_mfma_f32_16x16x32_bf16 v[82:85], v[186:189], v[210:213], v[82:85]
	v_mfma_f32_16x16x32_bf16 v[70:73], v[178:181], v[218:221], v[70:73]
	v_mfma_f32_16x16x32_bf16 v[66:69], v[186:189], v[218:221], v[66:69]
	s_setprio 1
	s_barrier
	s_add_i32 s60, s50, s41
	v_lshl_add_u64 v[150:151], s[30:31], 0, v[132:133]
	s_mov_b32 m0, s60
	ds_read_b128 v[190:193], v157 offset:16384
	ds_read_b128 v[194:197], v157 offset:17408
	ds_read_b128 v[198:201], v157 offset:18432
	ds_read_b128 v[202:205], v157 offset:19456
	ds_read_b128 v[206:209], v157 offset:20480
	ds_read_b128 v[210:213], v157 offset:21504
	ds_read_b128 v[214:217], v157 offset:22528
	ds_read_b128 v[218:221], v157 offset:23552
	global_load_lds_dwordx4 v[150:151], off
	s_add_i32 m0, s60, 0x2000
	s_add_u32 s60, s30, 0x40000
	v_lshl_add_u64 v[222:223], s[30:31], 0, v[136:137]
	s_addc_u32 s61, s31, 0
	s_add_i32 s62, s51, s41
	global_load_lds_dwordx4 v[222:223], off
	v_lshl_add_u64 v[224:225], s[60:61], 0, v[132:133]
	s_mov_b32 m0, s62
	v_lshl_add_u64 v[226:227], s[34:35], 0, v[134:135]
	global_load_lds_dwordx4 v[224:225], off
	v_lshl_add_u64 v[224:225], s[60:61], 0, v[136:137]
	s_add_i32 m0, s62, 0x2000
	s_nop 0
	global_load_lds_dwordx4 v[224:225], off
	v_lshl_add_u64 v[224:225], s[34:35], 0, v[130:131]
	s_mov_b32 m0, s23
	s_nop 0
	global_load_lds_dwordx4 v[224:225], off
	s_mov_b32 m0, s42
	s_nop 0
	global_load_lds_dwordx4 v[226:227], off
	s_cmp_eq_u32 s59, 0
	s_cbranch_scc1 .Lw8_3
	s_waitcnt vmcnt(24)
	s_branch .Lwe_3

.Lwe_3:
	s_waitcnt lgkmcnt(0)
	s_barrier
	s_setprio 0
	s_waitcnt lgkmcnt(0)
	v_mfma_f32_16x16x32_bf16 v[62:65], v[158:161], v[190:193], v[62:65]
	v_mfma_f32_16x16x32_bf16 v[58:61], v[166:169], v[190:193], v[58:61]
	v_mfma_f32_16x16x32_bf16 v[46:49], v[158:161], v[198:201], v[46:49]
	v_mfma_f32_16x16x32_bf16 v[42:45], v[166:169], v[198:201], v[42:45]
	v_mfma_f32_16x16x32_bf16 v[30:33], v[158:161], v[206:209], v[30:33]
	v_mfma_f32_16x16x32_bf16 v[26:29], v[166:169], v[206:209], v[26:29]
	v_mfma_f32_16x16x32_bf16 v[14:17], v[158:161], v[214:217], v[14:17]
	v_mfma_f32_16x16x32_bf16 v[10:13], v[166:169], v[214:217], v[10:13]
	v_mfma_f32_16x16x32_bf16 v[62:65], v[162:165], v[194:197], v[62:65]
	v_mfma_f32_16x16x32_bf16 v[58:61], v[170:173], v[194:197], v[58:61]
	v_mfma_f32_16x16x32_bf16 v[46:49], v[162:165], v[202:205], v[46:49]
	v_mfma_f32_16x16x32_bf16 v[42:45], v[170:173], v[202:205], v[42:45]
	v_mfma_f32_16x16x32_bf16 v[30:33], v[162:165], v[210:213], v[30:33]
	v_mfma_f32_16x16x32_bf16 v[26:29], v[170:173], v[210:213], v[26:29]
	v_mfma_f32_16x16x32_bf16 v[14:17], v[162:165], v[218:221], v[14:17]
	v_mfma_f32_16x16x32_bf16 v[10:13], v[170:173], v[218:221], v[10:13]
	s_setprio 1
	s_setprio 0
	v_mfma_f32_16x16x32_bf16 v[54:57], v[174:177], v[190:193], v[54:57]
	v_mfma_f32_16x16x32_bf16 v[50:53], v[182:185], v[190:193], v[50:53]
	v_mfma_f32_16x16x32_bf16 v[38:41], v[174:177], v[198:201], v[38:41]
	v_mfma_f32_16x16x32_bf16 v[34:37], v[182:185], v[198:201], v[34:37]
	v_mfma_f32_16x16x32_bf16 v[22:25], v[174:177], v[206:209], v[22:25]
	v_mfma_f32_16x16x32_bf16 v[18:21], v[182:185], v[206:209], v[18:21]
	v_mfma_f32_16x16x32_bf16 v[6:9], v[174:177], v[214:217], v[6:9]
	v_mfma_f32_16x16x32_bf16 v[2:5], v[182:185], v[214:217], v[2:5]
	v_mfma_f32_16x16x32_bf16 v[54:57], v[178:181], v[194:197], v[54:57]
	v_mfma_f32_16x16x32_bf16 v[50:53], v[186:189], v[194:197], v[50:53]
	v_mfma_f32_16x16x32_bf16 v[38:41], v[178:181], v[202:205], v[38:41]
	v_mfma_f32_16x16x32_bf16 v[34:37], v[186:189], v[202:205], v[34:37]
	v_mfma_f32_16x16x32_bf16 v[22:25], v[178:181], v[210:213], v[22:25]
	v_mfma_f32_16x16x32_bf16 v[18:21], v[186:189], v[210:213], v[18:21]
	v_mfma_f32_16x16x32_bf16 v[6:9], v[178:181], v[218:221], v[6:9]
	v_mfma_f32_16x16x32_bf16 v[2:5], v[186:189], v[218:221], v[2:5]
	s_setprio 1
	s_barrier
	s_add_i32 s59, 0, 0x18000
	s_add_i32 s60, 0, 0x1c000
	v_add_u32_e32 v170, s59, v152
	v_add_u32_e32 v186, s60, v152
	ds_read_b128 v[158:161], v170
	ds_read_b128 v[162:165], v170 offset:1024
	ds_read_b128 v[166:169], v170 offset:2048
	ds_read_b128 v[170:173], v170 offset:3072
	ds_read_b128 v[174:177], v186
	ds_read_b128 v[178:181], v186 offset:1024
	ds_read_b128 v[182:185], v186 offset:2048
	ds_read_b128 v[186:189], v186 offset:3072
	s_add_u32 s34, s34, 0x40000
	s_addc_u32 s35, s35, 0
	s_mov_b32 m0, s43
	v_lshl_add_u64 v[228:229], s[34:35], 0, v[130:131]
	ds_read_b128 v[190:193], v157 offset:32768
	ds_read_b128 v[194:197], v157 offset:33792
	ds_read_b128 v[198:201], v157 offset:34816
	ds_read_b128 v[202:205], v157 offset:35840
	ds_read_b128 v[206:209], v157 offset:36864
	ds_read_b128 v[210:213], v157 offset:37888
	ds_read_b128 v[214:217], v157 offset:38912
	ds_read_b128 v[218:221], v157 offset:39936
	global_load_lds_dwordx4 v[228:229], off
	v_lshl_add_u64 v[228:229], s[34:35], 0, v[134:135]
	s_mov_b32 m0, s44
	s_nop 0
	global_load_lds_dwordx4 v[228:229], off
	s_waitcnt vmcnt(8)
	s_waitcnt lgkmcnt(0)
	s_barrier
	s_setprio 0
	s_waitcnt lgkmcnt(0)
	v_mfma_f32_16x16x32_bf16 v[126:129], v[158:161], v[190:193], v[126:129]
	v_mfma_f32_16x16x32_bf16 v[122:125], v[166:169], v[190:193], v[122:125]
	v_mfma_f32_16x16x32_bf16 v[110:113], v[158:161], v[198:201], v[110:113]
	v_mfma_f32_16x16x32_bf16 v[106:109], v[166:169], v[198:201], v[106:109]
	v_mfma_f32_16x16x32_bf16 v[94:97], v[158:161], v[206:209], v[94:97]
	v_mfma_f32_16x16x32_bf16 v[90:93], v[166:169], v[206:209], v[90:93]
	v_mfma_f32_16x16x32_bf16 v[78:81], v[158:161], v[214:217], v[78:81]
	v_mfma_f32_16x16x32_bf16 v[74:77], v[166:169], v[214:217], v[74:77]
	v_mfma_f32_16x16x32_bf16 v[126:129], v[162:165], v[194:197], v[126:129]
	v_mfma_f32_16x16x32_bf16 v[122:125], v[170:173], v[194:197], v[122:125]
	v_mfma_f32_16x16x32_bf16 v[110:113], v[162:165], v[202:205], v[110:113]
	v_mfma_f32_16x16x32_bf16 v[106:109], v[170:173], v[202:205], v[106:109]
	v_mfma_f32_16x16x32_bf16 v[94:97], v[162:165], v[210:213], v[94:97]
	v_mfma_f32_16x16x32_bf16 v[90:93], v[170:173], v[210:213], v[90:93]
	v_mfma_f32_16x16x32_bf16 v[78:81], v[162:165], v[218:221], v[78:81]
	v_mfma_f32_16x16x32_bf16 v[74:77], v[170:173], v[218:221], v[74:77]
	s_setprio 1
	s_setprio 0
	v_mfma_f32_16x16x32_bf16 v[118:121], v[174:177], v[190:193], v[118:121]
	v_mfma_f32_16x16x32_bf16 v[114:117], v[182:185], v[190:193], v[114:117]
	v_mfma_f32_16x16x32_bf16 v[102:105], v[174:177], v[198:201], v[102:105]
	v_mfma_f32_16x16x32_bf16 v[98:101], v[182:185], v[198:201], v[98:101]
	v_mfma_f32_16x16x32_bf16 v[86:89], v[174:177], v[206:209], v[86:89]
	v_mfma_f32_16x16x32_bf16 v[82:85], v[182:185], v[206:209], v[82:85]
	v_mfma_f32_16x16x32_bf16 v[70:73], v[174:177], v[214:217], v[70:73]
	v_mfma_f32_16x16x32_bf16 v[66:69], v[182:185], v[214:217], v[66:69]
	v_mfma_f32_16x16x32_bf16 v[118:121], v[178:181], v[194:197], v[118:121]
	v_mfma_f32_16x16x32_bf16 v[114:117], v[186:189], v[194:197], v[114:117]
	v_mfma_f32_16x16x32_bf16 v[102:105], v[178:181], v[202:205], v[102:105]
	v_mfma_f32_16x16x32_bf16 v[98:101], v[186:189], v[202:205], v[98:101]
	v_mfma_f32_16x16x32_bf16 v[86:89], v[178:181], v[210:213], v[86:89]
	v_mfma_f32_16x16x32_bf16 v[82:85], v[186:189], v[210:213], v[82:85]
	v_mfma_f32_16x16x32_bf16 v[70:73], v[178:181], v[218:221], v[70:73]
	v_mfma_f32_16x16x32_bf16 v[66:69], v[186:189], v[218:221], v[66:69]
	s_setprio 1
	s_barrier
	s_add_i32 s34, s59, s41
	v_lshl_add_u64 v[150:151], v[150:151], 0, s[10:11]
	s_mov_b32 m0, s34
	ds_read_b128 v[190:193], v157 offset:49152
	ds_read_b128 v[194:197], v157 offset:50176
	ds_read_b128 v[198:201], v157 offset:51200
	ds_read_b128 v[202:205], v157 offset:52224
	ds_read_b128 v[206:209], v157 offset:53248
	ds_read_b128 v[210:213], v157 offset:54272
	ds_read_b128 v[214:217], v157 offset:55296
	ds_read_b128 v[218:221], v157 offset:56320
	global_load_lds_dwordx4 v[150:151], off
	s_add_i32 m0, s34, 0x2000
	s_add_u32 s30, s30, 0x40080
	v_lshl_add_u64 v[150:151], v[222:223], 0, s[10:11]
	s_addc_u32 s31, s31, 0
	s_add_i32 s34, s60, s41
	global_load_lds_dwordx4 v[150:151], off
	v_lshl_add_u64 v[150:151], s[30:31], 0, v[132:133]
	s_mov_b32 m0, s34
	s_nop 0
	global_load_lds_dwordx4 v[150:151], off
	v_lshl_add_u64 v[150:151], s[30:31], 0, v[136:137]
	s_add_i32 m0, s34, 0x2000
	s_nop 0
	global_load_lds_dwordx4 v[150:151], off
	v_lshl_add_u64 v[150:151], v[224:225], 0, s[10:11]
	s_mov_b32 m0, s46
	s_nop 0
	global_load_lds_dwordx4 v[150:151], off
	v_lshl_add_u64 v[150:151], v[226:227], 0, s[10:11]
	s_mov_b32 m0, s47
	s_nop 0
	global_load_lds_dwordx4 v[150:151], off
	s_waitcnt vmcnt(8)
	s_waitcnt lgkmcnt(0)
	s_barrier
	s_setprio 0
	s_waitcnt lgkmcnt(0)
	v_mfma_f32_16x16x32_bf16 v[62:65], v[158:161], v[190:193], v[62:65]
	v_mfma_f32_16x16x32_bf16 v[58:61], v[166:169], v[190:193], v[58:61]
	v_mfma_f32_16x16x32_bf16 v[46:49], v[158:161], v[198:201], v[46:49]
	v_mfma_f32_16x16x32_bf16 v[42:45], v[166:169], v[198:201], v[42:45]
	v_mfma_f32_16x16x32_bf16 v[30:33], v[158:161], v[206:209], v[30:33]
	v_mfma_f32_16x16x32_bf16 v[26:29], v[166:169], v[206:209], v[26:29]
	v_mfma_f32_16x16x32_bf16 v[14:17], v[158:161], v[214:217], v[14:17]
	v_mfma_f32_16x16x32_bf16 v[10:13], v[166:169], v[214:217], v[10:13]
	v_mfma_f32_16x16x32_bf16 v[62:65], v[162:165], v[194:197], v[62:65]
	v_mfma_f32_16x16x32_bf16 v[58:61], v[170:173], v[194:197], v[58:61]
	v_mfma_f32_16x16x32_bf16 v[46:49], v[162:165], v[202:205], v[46:49]
	v_mfma_f32_16x16x32_bf16 v[42:45], v[170:173], v[202:205], v[42:45]
	v_mfma_f32_16x16x32_bf16 v[30:33], v[162:165], v[210:213], v[30:33]
	v_mfma_f32_16x16x32_bf16 v[26:29], v[170:173], v[210:213], v[26:29]
	v_mfma_f32_16x16x32_bf16 v[14:17], v[162:165], v[218:221], v[14:17]
	v_mfma_f32_16x16x32_bf16 v[10:13], v[170:173], v[218:221], v[10:13]
	s_setprio 1
	s_setprio 0
	v_mfma_f32_16x16x32_bf16 v[54:57], v[174:177], v[190:193], v[54:57]
	v_mfma_f32_16x16x32_bf16 v[50:53], v[182:185], v[190:193], v[50:53]
	v_mfma_f32_16x16x32_bf16 v[38:41], v[174:177], v[198:201], v[38:41]
	v_mfma_f32_16x16x32_bf16 v[34:37], v[182:185], v[198:201], v[34:37]
	v_mfma_f32_16x16x32_bf16 v[22:25], v[174:177], v[206:209], v[22:25]
	v_mfma_f32_16x16x32_bf16 v[18:21], v[182:185], v[206:209], v[18:21]
	v_mfma_f32_16x16x32_bf16 v[6:9], v[174:177], v[214:217], v[6:9]
	v_mfma_f32_16x16x32_bf16 v[2:5], v[182:185], v[214:217], v[2:5]
	v_mfma_f32_16x16x32_bf16 v[54:57], v[178:181], v[194:197], v[54:57]
	v_mfma_f32_16x16x32_bf16 v[50:53], v[186:189], v[194:197], v[50:53]
	v_mfma_f32_16x16x32_bf16 v[38:41], v[178:181], v[202:205], v[38:41]
	v_mfma_f32_16x16x32_bf16 v[34:37], v[186:189], v[202:205], v[34:37]
	v_mfma_f32_16x16x32_bf16 v[22:25], v[178:181], v[210:213], v[22:25]
	v_mfma_f32_16x16x32_bf16 v[18:21], v[186:189], v[210:213], v[18:21]
	v_mfma_f32_16x16x32_bf16 v[6:9], v[178:181], v[218:221], v[6:9]
	v_mfma_f32_16x16x32_bf16 v[2:5], v[186:189], v[218:221], v[2:5]
	s_setprio 1
	s_barrier
	s_add_i32 s58, s58, 2
	s_add_u32 s28, s28, 0x100
	s_addc_u32 s29, s29, 0
	s_cmp_gt_u32 s58, 13
	s_cbranch_scc0 .LBB0_891
	s_and_b64 vcc, exec, s[12:13]
	s_cbranch_vccz .LBB0_894
	s_barrier

.Lwe_4:
	s_waitcnt lgkmcnt(0)
	s_barrier
	s_setprio 0
	s_waitcnt lgkmcnt(0)
	v_mfma_f32_16x16x32_bf16 v[126:129], v[150:153], v[188:191], v[126:129]
	v_mfma_f32_16x16x32_bf16 v[122:125], v[164:167], v[188:191], v[122:125]
	v_mfma_f32_16x16x32_bf16 v[110:113], v[150:153], v[196:199], v[110:113]
	v_mfma_f32_16x16x32_bf16 v[106:109], v[164:167], v[196:199], v[106:109]
	v_mfma_f32_16x16x32_bf16 v[94:97], v[150:153], v[204:207], v[94:97]
	v_mfma_f32_16x16x32_bf16 v[90:93], v[164:167], v[204:207], v[90:93]
	v_mfma_f32_16x16x32_bf16 v[78:81], v[150:153], v[212:215], v[78:81]
	v_mfma_f32_16x16x32_bf16 v[74:77], v[164:167], v[212:215], v[74:77]
	v_mfma_f32_16x16x32_bf16 v[126:129], v[160:163], v[192:195], v[126:129]
	v_mfma_f32_16x16x32_bf16 v[122:125], v[168:171], v[192:195], v[122:125]
	v_mfma_f32_16x16x32_bf16 v[110:113], v[160:163], v[200:203], v[110:113]
	v_mfma_f32_16x16x32_bf16 v[106:109], v[168:171], v[200:203], v[106:109]
	v_mfma_f32_16x16x32_bf16 v[94:97], v[160:163], v[208:211], v[94:97]
	v_mfma_f32_16x16x32_bf16 v[90:93], v[168:171], v[208:211], v[90:93]
	v_mfma_f32_16x16x32_bf16 v[78:81], v[160:163], v[216:219], v[78:81]
	v_mfma_f32_16x16x32_bf16 v[74:77], v[168:171], v[216:219], v[74:77]
	s_setprio 1
	s_setprio 0
	v_mfma_f32_16x16x32_bf16 v[118:121], v[172:175], v[188:191], v[118:121]
	v_mfma_f32_16x16x32_bf16 v[114:117], v[180:183], v[188:191], v[114:117]
	v_mfma_f32_16x16x32_bf16 v[102:105], v[172:175], v[196:199], v[102:105]
	v_mfma_f32_16x16x32_bf16 v[98:101], v[180:183], v[196:199], v[98:101]
	v_mfma_f32_16x16x32_bf16 v[86:89], v[172:175], v[204:207], v[86:89]
	v_mfma_f32_16x16x32_bf16 v[82:85], v[180:183], v[204:207], v[82:85]
	v_mfma_f32_16x16x32_bf16 v[70:73], v[172:175], v[212:215], v[70:73]
	v_mfma_f32_16x16x32_bf16 v[66:69], v[180:183], v[212:215], v[66:69]
	v_mfma_f32_16x16x32_bf16 v[118:121], v[176:179], v[192:195], v[118:121]
	v_mfma_f32_16x16x32_bf16 v[114:117], v[184:187], v[192:195], v[114:117]
	v_mfma_f32_16x16x32_bf16 v[102:105], v[176:179], v[200:203], v[102:105]
	v_mfma_f32_16x16x32_bf16 v[98:101], v[184:187], v[200:203], v[98:101]
	v_mfma_f32_16x16x32_bf16 v[86:89], v[176:179], v[208:211], v[86:89]
	v_mfma_f32_16x16x32_bf16 v[82:85], v[184:187], v[208:211], v[82:85]
	v_mfma_f32_16x16x32_bf16 v[70:73], v[176:179], v[216:219], v[70:73]
	v_mfma_f32_16x16x32_bf16 v[66:69], v[184:187], v[216:219], v[66:69]
	s_setprio 1
	s_barrier
	s_add_i32 s60, s50, s41
	v_lshl_add_u64 v[220:221], s[30:31], 0, v[132:133]
	s_mov_b32 m0, s60
	ds_read_b128 v[188:191], v159 offset:16384
	ds_read_b128 v[192:195], v159 offset:17408
	ds_read_b128 v[196:199], v159 offset:18432
	ds_read_b128 v[200:203], v159 offset:19456
	ds_read_b128 v[204:207], v159 offset:20480
	ds_read_b128 v[208:211], v159 offset:21504
	ds_read_b128 v[212:215], v159 offset:22528
	ds_read_b128 v[216:219], v159 offset:23552
	global_load_lds_dwordx4 v[220:221], off
	s_add_i32 m0, s60, 0x2000
	s_add_u32 s60, s30, 0x40000
	v_lshl_add_u64 v[222:223], s[30:31], 0, v[136:137]
	s_addc_u32 s61, s31, 0
	s_add_i32 s62, s51, s41
	global_load_lds_dwordx4 v[222:223], off
	v_lshl_add_u64 v[224:225], s[60:61], 0, v[132:133]
	s_mov_b32 m0, s62
	v_lshl_add_u64 v[226:227], s[34:35], 0, v[134:135]
	global_load_lds_dwordx4 v[224:225], off
	v_lshl_add_u64 v[224:225], s[60:61], 0, v[136:137]
	s_add_i32 m0, s62, 0x2000
	s_nop 0
	global_load_lds_dwordx4 v[224:225], off
	v_lshl_add_u64 v[224:225], s[34:35], 0, v[130:131]
	s_mov_b32 m0, s23
	s_nop 0
	global_load_lds_dwordx4 v[224:225], off
	s_mov_b32 m0, s42
	s_nop 0
	global_load_lds_dwordx4 v[226:227], off
	s_cmp_eq_u32 s59, 0
	s_cbranch_scc1 .Lw8_5
	s_waitcnt vmcnt(24)
	s_branch .Lwe_5

.Lwe_5:
	s_waitcnt lgkmcnt(0)
	s_barrier
	s_setprio 0
	s_waitcnt lgkmcnt(0)
	v_mfma_f32_16x16x32_bf16 v[62:65], v[150:153], v[188:191], v[62:65]
	v_mfma_f32_16x16x32_bf16 v[58:61], v[164:167], v[188:191], v[58:61]
	v_mfma_f32_16x16x32_bf16 v[46:49], v[150:153], v[196:199], v[46:49]
	v_mfma_f32_16x16x32_bf16 v[42:45], v[164:167], v[196:199], v[42:45]
	v_mfma_f32_16x16x32_bf16 v[30:33], v[150:153], v[204:207], v[30:33]
	v_mfma_f32_16x16x32_bf16 v[26:29], v[164:167], v[204:207], v[26:29]
	v_mfma_f32_16x16x32_bf16 v[14:17], v[150:153], v[212:215], v[14:17]
	v_mfma_f32_16x16x32_bf16 v[10:13], v[164:167], v[212:215], v[10:13]
	v_mfma_f32_16x16x32_bf16 v[62:65], v[160:163], v[192:195], v[62:65]
	v_mfma_f32_16x16x32_bf16 v[58:61], v[168:171], v[192:195], v[58:61]
	v_mfma_f32_16x16x32_bf16 v[46:49], v[160:163], v[200:203], v[46:49]
	v_mfma_f32_16x16x32_bf16 v[42:45], v[168:171], v[200:203], v[42:45]
	v_mfma_f32_16x16x32_bf16 v[30:33], v[160:163], v[208:211], v[30:33]
	v_mfma_f32_16x16x32_bf16 v[26:29], v[168:171], v[208:211], v[26:29]
	v_mfma_f32_16x16x32_bf16 v[14:17], v[160:163], v[216:219], v[14:17]
	v_mfma_f32_16x16x32_bf16 v[10:13], v[168:171], v[216:219], v[10:13]
	s_setprio 1
	s_setprio 0
	v_mfma_f32_16x16x32_bf16 v[54:57], v[172:175], v[188:191], v[54:57]
	v_mfma_f32_16x16x32_bf16 v[50:53], v[180:183], v[188:191], v[50:53]
	v_mfma_f32_16x16x32_bf16 v[38:41], v[172:175], v[196:199], v[38:41]
	v_mfma_f32_16x16x32_bf16 v[34:37], v[180:183], v[196:199], v[34:37]
	v_mfma_f32_16x16x32_bf16 v[22:25], v[172:175], v[204:207], v[22:25]
	v_mfma_f32_16x16x32_bf16 v[18:21], v[180:183], v[204:207], v[18:21]
	v_mfma_f32_16x16x32_bf16 v[6:9], v[172:175], v[212:215], v[6:9]
	v_mfma_f32_16x16x32_bf16 v[2:5], v[180:183], v[212:215], v[2:5]
	v_mfma_f32_16x16x32_bf16 v[54:57], v[176:179], v[192:195], v[54:57]
	v_mfma_f32_16x16x32_bf16 v[50:53], v[184:187], v[192:195], v[50:53]
	v_mfma_f32_16x16x32_bf16 v[38:41], v[176:179], v[200:203], v[38:41]
	v_mfma_f32_16x16x32_bf16 v[34:37], v[184:187], v[200:203], v[34:37]
	v_mfma_f32_16x16x32_bf16 v[22:25], v[176:179], v[208:211], v[22:25]
	v_mfma_f32_16x16x32_bf16 v[18:21], v[184:187], v[208:211], v[18:21]
	v_mfma_f32_16x16x32_bf16 v[6:9], v[176:179], v[216:219], v[6:9]
	v_mfma_f32_16x16x32_bf16 v[2:5], v[184:187], v[216:219], v[2:5]
	s_setprio 1
	s_barrier
	s_add_i32 s59, 0, 0x18000
	s_add_i32 s60, 0, 0x1c000
	v_add_u32_e32 v168, s59, v155
	v_add_u32_e32 v184, s60, v155
	ds_read_b128 v[150:153], v168
	ds_read_b128 v[160:163], v168 offset:1024
	ds_read_b128 v[164:167], v168 offset:2048
	ds_read_b128 v[168:171], v168 offset:3072
	ds_read_b128 v[172:175], v184
	ds_read_b128 v[176:179], v184 offset:1024
	ds_read_b128 v[180:183], v184 offset:2048
	ds_read_b128 v[184:187], v184 offset:3072
	s_add_u32 s34, s34, 0x40000
	s_addc_u32 s35, s35, 0
	s_mov_b32 m0, s43
	v_lshl_add_u64 v[228:229], s[34:35], 0, v[130:131]
	ds_read_b128 v[188:191], v159 offset:32768
	ds_read_b128 v[192:195], v159 offset:33792
	ds_read_b128 v[196:199], v159 offset:34816
	ds_read_b128 v[200:203], v159 offset:35840
	ds_read_b128 v[204:207], v159 offset:36864
	ds_read_b128 v[208:211], v159 offset:37888
	ds_read_b128 v[212:215], v159 offset:38912
	ds_read_b128 v[216:219], v159 offset:39936
	global_load_lds_dwordx4 v[228:229], off
	v_lshl_add_u64 v[228:229], s[34:35], 0, v[134:135]
	s_mov_b32 m0, s44
	s_nop 0
	global_load_lds_dwordx4 v[228:229], off
	s_waitcnt vmcnt(8)
	s_waitcnt lgkmcnt(0)
	s_barrier
	s_setprio 0
	s_waitcnt lgkmcnt(0)
	v_mfma_f32_16x16x32_bf16 v[126:129], v[150:153], v[188:191], v[126:129]
	v_mfma_f32_16x16x32_bf16 v[122:125], v[164:167], v[188:191], v[122:125]
	v_mfma_f32_16x16x32_bf16 v[110:113], v[150:153], v[196:199], v[110:113]
	v_mfma_f32_16x16x32_bf16 v[106:109], v[164:167], v[196:199], v[106:109]
	v_mfma_f32_16x16x32_bf16 v[94:97], v[150:153], v[204:207], v[94:97]
	v_mfma_f32_16x16x32_bf16 v[90:93], v[164:167], v[204:207], v[90:93]
	v_mfma_f32_16x16x32_bf16 v[78:81], v[150:153], v[212:215], v[78:81]
	v_mfma_f32_16x16x32_bf16 v[74:77], v[164:167], v[212:215], v[74:77]
	v_mfma_f32_16x16x32_bf16 v[126:129], v[160:163], v[192:195], v[126:129]
	v_mfma_f32_16x16x32_bf16 v[122:125], v[168:171], v[192:195], v[122:125]
	v_mfma_f32_16x16x32_bf16 v[110:113], v[160:163], v[200:203], v[110:113]
	v_mfma_f32_16x16x32_bf16 v[106:109], v[168:171], v[200:203], v[106:109]
	v_mfma_f32_16x16x32_bf16 v[94:97], v[160:163], v[208:211], v[94:97]
	v_mfma_f32_16x16x32_bf16 v[90:93], v[168:171], v[208:211], v[90:93]
	v_mfma_f32_16x16x32_bf16 v[78:81], v[160:163], v[216:219], v[78:81]
	v_mfma_f32_16x16x32_bf16 v[74:77], v[168:171], v[216:219], v[74:77]
	s_setprio 1
	s_setprio 0
	v_mfma_f32_16x16x32_bf16 v[118:121], v[172:175], v[188:191], v[118:121]
	v_mfma_f32_16x16x32_bf16 v[114:117], v[180:183], v[188:191], v[114:117]
	v_mfma_f32_16x16x32_bf16 v[102:105], v[172:175], v[196:199], v[102:105]
	v_mfma_f32_16x16x32_bf16 v[98:101], v[180:183], v[196:199], v[98:101]
	v_mfma_f32_16x16x32_bf16 v[86:89], v[172:175], v[204:207], v[86:89]
	v_mfma_f32_16x16x32_bf16 v[82:85], v[180:183], v[204:207], v[82:85]
	v_mfma_f32_16x16x32_bf16 v[70:73], v[172:175], v[212:215], v[70:73]
	v_mfma_f32_16x16x32_bf16 v[66:69], v[180:183], v[212:215], v[66:69]
	v_mfma_f32_16x16x32_bf16 v[118:121], v[176:179], v[192:195], v[118:121]
	v_mfma_f32_16x16x32_bf16 v[114:117], v[184:187], v[192:195], v[114:117]
	v_mfma_f32_16x16x32_bf16 v[102:105], v[176:179], v[200:203], v[102:105]
	v_mfma_f32_16x16x32_bf16 v[98:101], v[184:187], v[200:203], v[98:101]
	v_mfma_f32_16x16x32_bf16 v[86:89], v[176:179], v[208:211], v[86:89]
	v_mfma_f32_16x16x32_bf16 v[82:85], v[184:187], v[208:211], v[82:85]
	v_mfma_f32_16x16x32_bf16 v[70:73], v[176:179], v[216:219], v[70:73]
	v_mfma_f32_16x16x32_bf16 v[66:69], v[184:187], v[216:219], v[66:69]
	s_setprio 1
	s_barrier
	s_add_i32 s34, s59, s41
	v_lshl_add_u64 v[220:221], v[220:221], 0, s[10:11]
	s_mov_b32 m0, s34
	ds_read_b128 v[188:191], v159 offset:49152
	ds_read_b128 v[192:195], v159 offset:50176
	ds_read_b128 v[196:199], v159 offset:51200
	ds_read_b128 v[200:203], v159 offset:52224
	ds_read_b128 v[204:207], v159 offset:53248
	ds_read_b128 v[208:211], v159 offset:54272
	ds_read_b128 v[212:215], v159 offset:55296
	ds_read_b128 v[216:219], v159 offset:56320
	global_load_lds_dwordx4 v[220:221], off
	s_add_i32 m0, s34, 0x2000
	s_add_u32 s30, s30, 0x40080
	v_lshl_add_u64 v[220:221], v[222:223], 0, s[10:11]
	s_addc_u32 s31, s31, 0
	s_add_i32 s34, s60, s41
	global_load_lds_dwordx4 v[220:221], off
	v_lshl_add_u64 v[220:221], s[30:31], 0, v[132:133]
	s_mov_b32 m0, s34
	s_nop 0
	global_load_lds_dwordx4 v[220:221], off
	v_lshl_add_u64 v[220:221], s[30:31], 0, v[136:137]
	s_add_i32 m0, s34, 0x2000
	s_nop 0
	global_load_lds_dwordx4 v[220:221], off
	v_lshl_add_u64 v[220:221], v[224:225], 0, s[10:11]
	s_mov_b32 m0, s46
	s_nop 0
	global_load_lds_dwordx4 v[220:221], off
	v_lshl_add_u64 v[220:221], v[226:227], 0, s[10:11]
	s_mov_b32 m0, s47
	s_nop 0
	global_load_lds_dwordx4 v[220:221], off
	s_waitcnt vmcnt(8)
	s_waitcnt lgkmcnt(0)
	s_barrier
	s_setprio 0
	s_waitcnt lgkmcnt(0)
	v_mfma_f32_16x16x32_bf16 v[62:65], v[150:153], v[188:191], v[62:65]
	v_mfma_f32_16x16x32_bf16 v[58:61], v[164:167], v[188:191], v[58:61]
	v_mfma_f32_16x16x32_bf16 v[46:49], v[150:153], v[196:199], v[46:49]
	v_mfma_f32_16x16x32_bf16 v[42:45], v[164:167], v[196:199], v[42:45]
	v_mfma_f32_16x16x32_bf16 v[30:33], v[150:153], v[204:207], v[30:33]
	v_mfma_f32_16x16x32_bf16 v[26:29], v[164:167], v[204:207], v[26:29]
	v_mfma_f32_16x16x32_bf16 v[14:17], v[150:153], v[212:215], v[14:17]
	v_mfma_f32_16x16x32_bf16 v[10:13], v[164:167], v[212:215], v[10:13]
	v_mfma_f32_16x16x32_bf16 v[62:65], v[160:163], v[192:195], v[62:65]
	v_mfma_f32_16x16x32_bf16 v[58:61], v[168:171], v[192:195], v[58:61]
	v_mfma_f32_16x16x32_bf16 v[46:49], v[160:163], v[200:203], v[46:49]
	v_mfma_f32_16x16x32_bf16 v[42:45], v[168:171], v[200:203], v[42:45]
	v_mfma_f32_16x16x32_bf16 v[30:33], v[160:163], v[208:211], v[30:33]
	v_mfma_f32_16x16x32_bf16 v[26:29], v[168:171], v[208:211], v[26:29]
	v_mfma_f32_16x16x32_bf16 v[14:17], v[160:163], v[216:219], v[14:17]
	v_mfma_f32_16x16x32_bf16 v[10:13], v[168:171], v[216:219], v[10:13]
	s_setprio 1
	s_setprio 0
	v_mfma_f32_16x16x32_bf16 v[54:57], v[172:175], v[188:191], v[54:57]
	v_mfma_f32_16x16x32_bf16 v[50:53], v[180:183], v[188:191], v[50:53]
	v_mfma_f32_16x16x32_bf16 v[38:41], v[172:175], v[196:199], v[38:41]
	v_mfma_f32_16x16x32_bf16 v[34:37], v[180:183], v[196:199], v[34:37]
	v_mfma_f32_16x16x32_bf16 v[22:25], v[172:175], v[204:207], v[22:25]
	v_mfma_f32_16x16x32_bf16 v[18:21], v[180:183], v[204:207], v[18:21]
	v_mfma_f32_16x16x32_bf16 v[6:9], v[172:175], v[212:215], v[6:9]
	v_mfma_f32_16x16x32_bf16 v[2:5], v[180:183], v[212:215], v[2:5]
	v_mfma_f32_16x16x32_bf16 v[54:57], v[176:179], v[192:195], v[54:57]
	v_mfma_f32_16x16x32_bf16 v[50:53], v[184:187], v[192:195], v[50:53]
	v_mfma_f32_16x16x32_bf16 v[38:41], v[176:179], v[200:203], v[38:41]
	v_mfma_f32_16x16x32_bf16 v[34:37], v[184:187], v[200:203], v[34:37]
	v_mfma_f32_16x16x32_bf16 v[22:25], v[176:179], v[208:211], v[22:25]
	v_mfma_f32_16x16x32_bf16 v[18:21], v[184:187], v[208:211], v[18:21]
	v_mfma_f32_16x16x32_bf16 v[6:9], v[176:179], v[216:219], v[6:9]
	v_mfma_f32_16x16x32_bf16 v[2:5], v[184:187], v[216:219], v[2:5]
	s_setprio 1
	s_barrier
	s_add_i32 s58, s58, 2
	s_add_u32 s28, s28, 0x100
	s_addc_u32 s29, s29, 0
	s_cmp_gt_u32 s58, 13
	s_cbranch_scc0 .LBB0_915
	s_and_b64 vcc, exec, s[12:13]
	s_cbranch_vccz .LBB0_918
	s_barrier

.Lwe_6:
	s_waitcnt lgkmcnt(0)
	s_barrier
	s_setprio 0
	s_waitcnt lgkmcnt(0)
	v_mfma_f32_16x16x32_bf16 v[126:129], v[156:159], v[188:191], v[126:129]
	v_mfma_f32_16x16x32_bf16 v[122:125], v[164:167], v[188:191], v[122:125]
	v_mfma_f32_16x16x32_bf16 v[118:121], v[156:159], v[196:199], v[118:121]
	v_mfma_f32_16x16x32_bf16 v[110:113], v[164:167], v[196:199], v[110:113]
	v_mfma_f32_16x16x32_bf16 v[102:105], v[156:159], v[204:207], v[102:105]
	v_mfma_f32_16x16x32_bf16 v[94:97], v[164:167], v[204:207], v[94:97]
	v_mfma_f32_16x16x32_bf16 v[86:89], v[156:159], v[212:215], v[86:89]
	v_mfma_f32_16x16x32_bf16 v[78:81], v[164:167], v[212:215], v[78:81]
	v_mfma_f32_16x16x32_bf16 v[126:129], v[160:163], v[192:195], v[126:129]
	v_mfma_f32_16x16x32_bf16 v[122:125], v[168:171], v[192:195], v[122:125]
	v_mfma_f32_16x16x32_bf16 v[118:121], v[160:163], v[200:203], v[118:121]
	v_mfma_f32_16x16x32_bf16 v[110:113], v[168:171], v[200:203], v[110:113]
	v_mfma_f32_16x16x32_bf16 v[102:105], v[160:163], v[208:211], v[102:105]
	v_mfma_f32_16x16x32_bf16 v[94:97], v[168:171], v[208:211], v[94:97]
	v_mfma_f32_16x16x32_bf16 v[86:89], v[160:163], v[216:219], v[86:89]
	v_mfma_f32_16x16x32_bf16 v[78:81], v[168:171], v[216:219], v[78:81]
	s_setprio 1
	s_setprio 0
	v_mfma_f32_16x16x32_bf16 v[114:117], v[172:175], v[188:191], v[114:117]
	v_mfma_f32_16x16x32_bf16 v[106:109], v[180:183], v[188:191], v[106:109]
	v_mfma_f32_16x16x32_bf16 v[98:101], v[172:175], v[196:199], v[98:101]
	v_mfma_f32_16x16x32_bf16 v[90:93], v[180:183], v[196:199], v[90:93]
	v_mfma_f32_16x16x32_bf16 v[82:85], v[172:175], v[204:207], v[82:85]
	v_mfma_f32_16x16x32_bf16 v[74:77], v[180:183], v[204:207], v[74:77]
	v_mfma_f32_16x16x32_bf16 v[70:73], v[172:175], v[212:215], v[70:73]
	v_mfma_f32_16x16x32_bf16 v[66:69], v[180:183], v[212:215], v[66:69]
	v_mfma_f32_16x16x32_bf16 v[114:117], v[176:179], v[192:195], v[114:117]
	v_mfma_f32_16x16x32_bf16 v[106:109], v[184:187], v[192:195], v[106:109]
	v_mfma_f32_16x16x32_bf16 v[98:101], v[176:179], v[200:203], v[98:101]
	v_mfma_f32_16x16x32_bf16 v[90:93], v[184:187], v[200:203], v[90:93]
	v_mfma_f32_16x16x32_bf16 v[82:85], v[176:179], v[208:211], v[82:85]
	v_mfma_f32_16x16x32_bf16 v[74:77], v[184:187], v[208:211], v[74:77]
	v_mfma_f32_16x16x32_bf16 v[70:73], v[176:179], v[216:219], v[70:73]
	v_mfma_f32_16x16x32_bf16 v[66:69], v[184:187], v[216:219], v[66:69]
	s_setprio 1
	s_barrier
	s_add_i32 s66, s53, s45
	v_lshl_add_u64 v[220:221], s[36:37], 0, v[132:133]
	s_mov_b32 m0, s66
	ds_read_b128 v[188:191], v155 offset:16384
	ds_read_b128 v[192:195], v155 offset:17408
	ds_read_b128 v[196:199], v155 offset:18432
	ds_read_b128 v[200:203], v155 offset:19456
	ds_read_b128 v[204:207], v155 offset:20480
	ds_read_b128 v[208:211], v155 offset:21504
	ds_read_b128 v[212:215], v155 offset:22528
	ds_read_b128 v[216:219], v155 offset:23552
	global_load_lds_dwordx4 v[220:221], off
	s_add_i32 m0, s66, 0x2000
	s_add_u32 s66, s36, 0x80000
	v_lshl_add_u64 v[222:223], s[36:37], 0, v[136:137]
	s_addc_u32 s67, s37, 0
	s_add_i32 s69, s54, s45
	global_load_lds_dwordx4 v[222:223], off
	v_lshl_add_u64 v[224:225], s[66:67], 0, v[132:133]
	s_mov_b32 m0, s69
	v_lshl_add_u64 v[226:227], s[38:39], 0, v[134:135]
	global_load_lds_dwordx4 v[224:225], off
	v_lshl_add_u64 v[224:225], s[66:67], 0, v[136:137]
	s_add_i32 m0, s69, 0x2000
	s_nop 0
	global_load_lds_dwordx4 v[224:225], off
	v_lshl_add_u64 v[224:225], s[38:39], 0, v[130:131]
	s_mov_b32 m0, s27
	s_nop 0
	global_load_lds_dwordx4 v[224:225], off
	s_mov_b32 m0, s46
	s_nop 0
	global_load_lds_dwordx4 v[226:227], off
	s_cmp_eq_u32 s68, 0
	s_cbranch_scc1 .Lw8_7
	s_waitcnt vmcnt(24)
	s_branch .Lwe_7

.Lwe_7:
	s_waitcnt lgkmcnt(0)
	s_barrier
	s_setprio 0
	s_waitcnt lgkmcnt(0)
	v_mfma_f32_16x16x32_bf16 v[62:65], v[156:159], v[188:191], v[62:65]
	v_mfma_f32_16x16x32_bf16 v[58:61], v[164:167], v[188:191], v[58:61]
	v_mfma_f32_16x16x32_bf16 v[54:57], v[156:159], v[196:199], v[54:57]
	v_mfma_f32_16x16x32_bf16 v[46:49], v[164:167], v[196:199], v[46:49]
	v_mfma_f32_16x16x32_bf16 v[38:41], v[156:159], v[204:207], v[38:41]
	v_mfma_f32_16x16x32_bf16 v[30:33], v[164:167], v[204:207], v[30:33]
	v_mfma_f32_16x16x32_bf16 v[22:25], v[156:159], v[212:215], v[22:25]
	v_mfma_f32_16x16x32_bf16 v[14:17], v[164:167], v[212:215], v[14:17]
	v_mfma_f32_16x16x32_bf16 v[62:65], v[160:163], v[192:195], v[62:65]
	v_mfma_f32_16x16x32_bf16 v[58:61], v[168:171], v[192:195], v[58:61]
	v_mfma_f32_16x16x32_bf16 v[54:57], v[160:163], v[200:203], v[54:57]
	v_mfma_f32_16x16x32_bf16 v[46:49], v[168:171], v[200:203], v[46:49]
	v_mfma_f32_16x16x32_bf16 v[38:41], v[160:163], v[208:211], v[38:41]
	v_mfma_f32_16x16x32_bf16 v[30:33], v[168:171], v[208:211], v[30:33]
	v_mfma_f32_16x16x32_bf16 v[22:25], v[160:163], v[216:219], v[22:25]
	v_mfma_f32_16x16x32_bf16 v[14:17], v[168:171], v[216:219], v[14:17]
	s_setprio 1
	s_setprio 0
	v_mfma_f32_16x16x32_bf16 v[50:53], v[172:175], v[188:191], v[50:53]
	v_mfma_f32_16x16x32_bf16 v[42:45], v[180:183], v[188:191], v[42:45]
	v_mfma_f32_16x16x32_bf16 v[34:37], v[172:175], v[196:199], v[34:37]
	v_mfma_f32_16x16x32_bf16 v[26:29], v[180:183], v[196:199], v[26:29]
	v_mfma_f32_16x16x32_bf16 v[18:21], v[172:175], v[204:207], v[18:21]
	v_mfma_f32_16x16x32_bf16 v[10:13], v[180:183], v[204:207], v[10:13]
	v_mfma_f32_16x16x32_bf16 v[6:9], v[172:175], v[212:215], v[6:9]
	v_mfma_f32_16x16x32_bf16 v[2:5], v[180:183], v[212:215], v[2:5]
	v_mfma_f32_16x16x32_bf16 v[50:53], v[176:179], v[192:195], v[50:53]
	v_mfma_f32_16x16x32_bf16 v[42:45], v[184:187], v[192:195], v[42:45]
	v_mfma_f32_16x16x32_bf16 v[34:37], v[176:179], v[200:203], v[34:37]
	v_mfma_f32_16x16x32_bf16 v[26:29], v[184:187], v[200:203], v[26:29]
	v_mfma_f32_16x16x32_bf16 v[18:21], v[176:179], v[208:211], v[18:21]
	v_mfma_f32_16x16x32_bf16 v[10:13], v[184:187], v[208:211], v[10:13]
	v_mfma_f32_16x16x32_bf16 v[6:9], v[176:179], v[216:219], v[6:9]
	v_mfma_f32_16x16x32_bf16 v[2:5], v[184:187], v[216:219], v[2:5]
	s_setprio 1
	s_barrier
	s_add_i32 s66, 0, 0x18000
	s_add_i32 s67, 0, 0x1c000
	v_add_u32_e32 v168, s66, v150
	v_add_u32_e32 v184, s67, v150
	ds_read_b128 v[156:159], v168
	ds_read_b128 v[160:163], v168 offset:1024
	ds_read_b128 v[164:167], v168 offset:2048
	ds_read_b128 v[168:171], v168 offset:3072
	ds_read_b128 v[172:175], v184
	ds_read_b128 v[176:179], v184 offset:1024
	ds_read_b128 v[180:183], v184 offset:2048
	ds_read_b128 v[184:187], v184 offset:3072
	s_add_u32 s38, s38, 0x80000
	s_addc_u32 s39, s39, 0
	s_mov_b32 m0, s47
	v_lshl_add_u64 v[228:229], s[38:39], 0, v[130:131]
	ds_read_b128 v[188:191], v155 offset:32768
	ds_read_b128 v[192:195], v155 offset:33792
	ds_read_b128 v[196:199], v155 offset:34816
	ds_read_b128 v[200:203], v155 offset:35840
	ds_read_b128 v[204:207], v155 offset:36864
	ds_read_b128 v[208:211], v155 offset:37888
	ds_read_b128 v[212:215], v155 offset:38912
	ds_read_b128 v[216:219], v155 offset:39936
	global_load_lds_dwordx4 v[228:229], off
	v_lshl_add_u64 v[228:229], s[38:39], 0, v[134:135]
	s_mov_b32 m0, s48
	s_nop 0
	global_load_lds_dwordx4 v[228:229], off
	s_waitcnt vmcnt(8)
	s_waitcnt lgkmcnt(0)
	s_barrier
	s_setprio 0
	s_waitcnt lgkmcnt(0)
	v_mfma_f32_16x16x32_bf16 v[126:129], v[156:159], v[188:191], v[126:129]
	v_mfma_f32_16x16x32_bf16 v[122:125], v[164:167], v[188:191], v[122:125]
	v_mfma_f32_16x16x32_bf16 v[118:121], v[156:159], v[196:199], v[118:121]
	v_mfma_f32_16x16x32_bf16 v[110:113], v[164:167], v[196:199], v[110:113]
	v_mfma_f32_16x16x32_bf16 v[102:105], v[156:159], v[204:207], v[102:105]
	v_mfma_f32_16x16x32_bf16 v[94:97], v[164:167], v[204:207], v[94:97]
	v_mfma_f32_16x16x32_bf16 v[86:89], v[156:159], v[212:215], v[86:89]
	v_mfma_f32_16x16x32_bf16 v[78:81], v[164:167], v[212:215], v[78:81]
	v_mfma_f32_16x16x32_bf16 v[126:129], v[160:163], v[192:195], v[126:129]
	v_mfma_f32_16x16x32_bf16 v[122:125], v[168:171], v[192:195], v[122:125]
	v_mfma_f32_16x16x32_bf16 v[118:121], v[160:163], v[200:203], v[118:121]
	v_mfma_f32_16x16x32_bf16 v[110:113], v[168:171], v[200:203], v[110:113]
	v_mfma_f32_16x16x32_bf16 v[102:105], v[160:163], v[208:211], v[102:105]
	v_mfma_f32_16x16x32_bf16 v[94:97], v[168:171], v[208:211], v[94:97]
	v_mfma_f32_16x16x32_bf16 v[86:89], v[160:163], v[216:219], v[86:89]
	v_mfma_f32_16x16x32_bf16 v[78:81], v[168:171], v[216:219], v[78:81]
	s_setprio 1
	s_setprio 0
	v_mfma_f32_16x16x32_bf16 v[114:117], v[172:175], v[188:191], v[114:117]
	v_mfma_f32_16x16x32_bf16 v[106:109], v[180:183], v[188:191], v[106:109]
	v_mfma_f32_16x16x32_bf16 v[98:101], v[172:175], v[196:199], v[98:101]
	v_mfma_f32_16x16x32_bf16 v[90:93], v[180:183], v[196:199], v[90:93]
	v_mfma_f32_16x16x32_bf16 v[82:85], v[172:175], v[204:207], v[82:85]
	v_mfma_f32_16x16x32_bf16 v[74:77], v[180:183], v[204:207], v[74:77]
	v_mfma_f32_16x16x32_bf16 v[70:73], v[172:175], v[212:215], v[70:73]
	v_mfma_f32_16x16x32_bf16 v[66:69], v[180:183], v[212:215], v[66:69]
	v_mfma_f32_16x16x32_bf16 v[114:117], v[176:179], v[192:195], v[114:117]
	v_mfma_f32_16x16x32_bf16 v[106:109], v[184:187], v[192:195], v[106:109]
	v_mfma_f32_16x16x32_bf16 v[98:101], v[176:179], v[200:203], v[98:101]
	v_mfma_f32_16x16x32_bf16 v[90:93], v[184:187], v[200:203], v[90:93]
	v_mfma_f32_16x16x32_bf16 v[82:85], v[176:179], v[208:211], v[82:85]
	v_mfma_f32_16x16x32_bf16 v[74:77], v[184:187], v[208:211], v[74:77]
	v_mfma_f32_16x16x32_bf16 v[70:73], v[176:179], v[216:219], v[70:73]
	v_mfma_f32_16x16x32_bf16 v[66:69], v[184:187], v[216:219], v[66:69]
	s_setprio 1
	s_barrier
	s_add_i32 s38, s66, s45
	v_lshl_add_u64 v[220:221], v[220:221], 0, s[8:9]
	s_mov_b32 m0, s38
	ds_read_b128 v[188:191], v155 offset:49152
	ds_read_b128 v[192:195], v155 offset:50176
	ds_read_b128 v[196:199], v155 offset:51200
	ds_read_b128 v[200:203], v155 offset:52224
	ds_read_b128 v[204:207], v155 offset:53248
	ds_read_b128 v[208:211], v155 offset:54272
	ds_read_b128 v[212:215], v155 offset:55296
	ds_read_b128 v[216:219], v155 offset:56320
	global_load_lds_dwordx4 v[220:221], off
	s_add_i32 m0, s38, 0x2000
	s_add_u32 s36, s36, 0x80080
	v_lshl_add_u64 v[220:221], v[222:223], 0, s[8:9]
	s_addc_u32 s37, s37, 0
	s_add_i32 s38, s67, s45
	global_load_lds_dwordx4 v[220:221], off
	v_lshl_add_u64 v[220:221], s[36:37], 0, v[132:133]
	s_mov_b32 m0, s38
	s_nop 0
	global_load_lds_dwordx4 v[220:221], off
	v_lshl_add_u64 v[220:221], s[36:37], 0, v[136:137]
	s_add_i32 m0, s38, 0x2000
	s_nop 0
	global_load_lds_dwordx4 v[220:221], off
	v_lshl_add_u64 v[220:221], v[224:225], 0, s[8:9]
	s_mov_b32 m0, s49
	s_nop 0
	global_load_lds_dwordx4 v[220:221], off
	v_lshl_add_u64 v[220:221], v[226:227], 0, s[8:9]
	s_mov_b32 m0, s50
	s_nop 0
	global_load_lds_dwordx4 v[220:221], off
	s_waitcnt vmcnt(8)
	s_waitcnt lgkmcnt(0)
	s_barrier
	s_setprio 0
	s_waitcnt lgkmcnt(0)
	v_mfma_f32_16x16x32_bf16 v[62:65], v[156:159], v[188:191], v[62:65]
	v_mfma_f32_16x16x32_bf16 v[58:61], v[164:167], v[188:191], v[58:61]
	v_mfma_f32_16x16x32_bf16 v[54:57], v[156:159], v[196:199], v[54:57]
	v_mfma_f32_16x16x32_bf16 v[46:49], v[164:167], v[196:199], v[46:49]
	v_mfma_f32_16x16x32_bf16 v[38:41], v[156:159], v[204:207], v[38:41]
	v_mfma_f32_16x16x32_bf16 v[30:33], v[164:167], v[204:207], v[30:33]
	v_mfma_f32_16x16x32_bf16 v[22:25], v[156:159], v[212:215], v[22:25]
	v_mfma_f32_16x16x32_bf16 v[14:17], v[164:167], v[212:215], v[14:17]
	v_mfma_f32_16x16x32_bf16 v[62:65], v[160:163], v[192:195], v[62:65]
	v_mfma_f32_16x16x32_bf16 v[58:61], v[168:171], v[192:195], v[58:61]
	v_mfma_f32_16x16x32_bf16 v[54:57], v[160:163], v[200:203], v[54:57]
	v_mfma_f32_16x16x32_bf16 v[46:49], v[168:171], v[200:203], v[46:49]
	v_mfma_f32_16x16x32_bf16 v[38:41], v[160:163], v[208:211], v[38:41]
	v_mfma_f32_16x16x32_bf16 v[30:33], v[168:171], v[208:211], v[30:33]
	v_mfma_f32_16x16x32_bf16 v[22:25], v[160:163], v[216:219], v[22:25]
	v_mfma_f32_16x16x32_bf16 v[14:17], v[168:171], v[216:219], v[14:17]
	s_setprio 1
	s_setprio 0
	v_mfma_f32_16x16x32_bf16 v[50:53], v[172:175], v[188:191], v[50:53]
	v_mfma_f32_16x16x32_bf16 v[42:45], v[180:183], v[188:191], v[42:45]
	v_mfma_f32_16x16x32_bf16 v[34:37], v[172:175], v[196:199], v[34:37]
	v_mfma_f32_16x16x32_bf16 v[26:29], v[180:183], v[196:199], v[26:29]
	v_mfma_f32_16x16x32_bf16 v[18:21], v[172:175], v[204:207], v[18:21]
	v_mfma_f32_16x16x32_bf16 v[10:13], v[180:183], v[204:207], v[10:13]
	v_mfma_f32_16x16x32_bf16 v[6:9], v[172:175], v[212:215], v[6:9]
	v_mfma_f32_16x16x32_bf16 v[2:5], v[180:183], v[212:215], v[2:5]
	v_mfma_f32_16x16x32_bf16 v[50:53], v[176:179], v[192:195], v[50:53]
	v_mfma_f32_16x16x32_bf16 v[42:45], v[184:187], v[192:195], v[42:45]
	v_mfma_f32_16x16x32_bf16 v[34:37], v[176:179], v[200:203], v[34:37]
	v_mfma_f32_16x16x32_bf16 v[26:29], v[184:187], v[200:203], v[26:29]
	v_mfma_f32_16x16x32_bf16 v[18:21], v[176:179], v[208:211], v[18:21]
	v_mfma_f32_16x16x32_bf16 v[10:13], v[184:187], v[208:211], v[10:13]
	v_mfma_f32_16x16x32_bf16 v[6:9], v[176:179], v[216:219], v[6:9]
	v_mfma_f32_16x16x32_bf16 v[2:5], v[184:187], v[216:219], v[2:5]
	s_setprio 1
	s_barrier
	s_add_i32 s65, s65, 2
	s_add_u32 s34, s34, 0x100
	s_addc_u32 s35, s35, 0
	s_cmp_gt_u32 s65, 29
	s_cbranch_scc0 .LBB0_1009
	s_and_b64 vcc, exec, s[10:11]
	s_cbranch_vccz .LBB0_1012
	s_barrier

.Lwe_8:
	s_waitcnt lgkmcnt(0)
	s_barrier
	s_setprio 0
	s_waitcnt lgkmcnt(0)
	v_mfma_f32_16x16x32_bf16 v[126:129], v[156:159], v[188:191], v[126:129]
	v_mfma_f32_16x16x32_bf16 v[122:125], v[164:167], v[188:191], v[122:125]
	v_mfma_f32_16x16x32_bf16 v[118:121], v[156:159], v[196:199], v[118:121]
	v_mfma_f32_16x16x32_bf16 v[110:113], v[164:167], v[196:199], v[110:113]
	v_mfma_f32_16x16x32_bf16 v[102:105], v[156:159], v[204:207], v[102:105]
	v_mfma_f32_16x16x32_bf16 v[94:97], v[164:167], v[204:207], v[94:97]
	v_mfma_f32_16x16x32_bf16 v[86:89], v[156:159], v[212:215], v[86:89]
	v_mfma_f32_16x16x32_bf16 v[78:81], v[164:167], v[212:215], v[78:81]
	v_mfma_f32_16x16x32_bf16 v[126:129], v[160:163], v[192:195], v[126:129]
	v_mfma_f32_16x16x32_bf16 v[122:125], v[168:171], v[192:195], v[122:125]
	v_mfma_f32_16x16x32_bf16 v[118:121], v[160:163], v[200:203], v[118:121]
	v_mfma_f32_16x16x32_bf16 v[110:113], v[168:171], v[200:203], v[110:113]
	v_mfma_f32_16x16x32_bf16 v[102:105], v[160:163], v[208:211], v[102:105]
	v_mfma_f32_16x16x32_bf16 v[94:97], v[168:171], v[208:211], v[94:97]
	v_mfma_f32_16x16x32_bf16 v[86:89], v[160:163], v[216:219], v[86:89]
	v_mfma_f32_16x16x32_bf16 v[78:81], v[168:171], v[216:219], v[78:81]
	s_setprio 1
	s_setprio 0
	v_mfma_f32_16x16x32_bf16 v[114:117], v[172:175], v[188:191], v[114:117]
	v_mfma_f32_16x16x32_bf16 v[106:109], v[180:183], v[188:191], v[106:109]
	v_mfma_f32_16x16x32_bf16 v[98:101], v[172:175], v[196:199], v[98:101]
	v_mfma_f32_16x16x32_bf16 v[90:93], v[180:183], v[196:199], v[90:93]
	v_mfma_f32_16x16x32_bf16 v[82:85], v[172:175], v[204:207], v[82:85]
	v_mfma_f32_16x16x32_bf16 v[74:77], v[180:183], v[204:207], v[74:77]
	v_mfma_f32_16x16x32_bf16 v[70:73], v[172:175], v[212:215], v[70:73]
	v_mfma_f32_16x16x32_bf16 v[66:69], v[180:183], v[212:215], v[66:69]
	v_mfma_f32_16x16x32_bf16 v[114:117], v[176:179], v[192:195], v[114:117]
	v_mfma_f32_16x16x32_bf16 v[106:109], v[184:187], v[192:195], v[106:109]
	v_mfma_f32_16x16x32_bf16 v[98:101], v[176:179], v[200:203], v[98:101]
	v_mfma_f32_16x16x32_bf16 v[90:93], v[184:187], v[200:203], v[90:93]
	v_mfma_f32_16x16x32_bf16 v[82:85], v[176:179], v[208:211], v[82:85]
	v_mfma_f32_16x16x32_bf16 v[74:77], v[184:187], v[208:211], v[74:77]
	v_mfma_f32_16x16x32_bf16 v[70:73], v[176:179], v[216:219], v[70:73]
	v_mfma_f32_16x16x32_bf16 v[66:69], v[184:187], v[216:219], v[66:69]
	s_setprio 1
	s_barrier
	s_add_i32 s56, s46, s36
	v_lshl_add_u64 v[220:221], s[26:27], 0, v[134:135]
	s_mov_b32 m0, s56
	ds_read_b128 v[188:191], v155 offset:16384
	ds_read_b128 v[192:195], v155 offset:17408
	ds_read_b128 v[196:199], v155 offset:18432
	ds_read_b128 v[200:203], v155 offset:19456
	ds_read_b128 v[204:207], v155 offset:20480
	ds_read_b128 v[208:211], v155 offset:21504
	ds_read_b128 v[212:215], v155 offset:22528
	ds_read_b128 v[216:219], v155 offset:23552
	global_load_lds_dwordx4 v[220:221], off
	s_add_i32 m0, s56, 0x2000
	s_add_u32 s56, s26, 0x80000
	v_lshl_add_u64 v[222:223], s[26:27], 0, v[130:131]
	s_addc_u32 s57, s27, 0
	s_add_i32 s59, s47, s36
	global_load_lds_dwordx4 v[222:223], off
	v_lshl_add_u64 v[224:225], s[56:57], 0, v[134:135]
	s_mov_b32 m0, s59
	v_lshl_add_u64 v[226:227], s[28:29], 0, v[132:133]
	global_load_lds_dwordx4 v[224:225], off
	v_lshl_add_u64 v[224:225], s[56:57], 0, v[130:131]
	s_add_i32 m0, s59, 0x2000
	s_nop 0
	global_load_lds_dwordx4 v[224:225], off
	v_lshl_add_u64 v[224:225], s[28:29], 0, v[136:137]
	s_mov_b32 m0, s19
	s_nop 0
	global_load_lds_dwordx4 v[224:225], off
	s_mov_b32 m0, s39
	s_nop 0
	global_load_lds_dwordx4 v[226:227], off
	s_cmp_eq_u32 s58, 0
	s_cbranch_scc1 .Lw8_9
	s_waitcnt vmcnt(24)
	s_branch .Lwe_9

.Lwe_9:
	s_waitcnt lgkmcnt(0)
	s_barrier
	s_setprio 0
	s_waitcnt lgkmcnt(0)
	v_mfma_f32_16x16x32_bf16 v[62:65], v[156:159], v[188:191], v[62:65]
	v_mfma_f32_16x16x32_bf16 v[58:61], v[164:167], v[188:191], v[58:61]
	v_mfma_f32_16x16x32_bf16 v[54:57], v[156:159], v[196:199], v[54:57]
	v_mfma_f32_16x16x32_bf16 v[46:49], v[164:167], v[196:199], v[46:49]
	v_mfma_f32_16x16x32_bf16 v[38:41], v[156:159], v[204:207], v[38:41]
	v_mfma_f32_16x16x32_bf16 v[30:33], v[164:167], v[204:207], v[30:33]
	v_mfma_f32_16x16x32_bf16 v[22:25], v[156:159], v[212:215], v[22:25]
	v_mfma_f32_16x16x32_bf16 v[14:17], v[164:167], v[212:215], v[14:17]
	v_mfma_f32_16x16x32_bf16 v[62:65], v[160:163], v[192:195], v[62:65]
	v_mfma_f32_16x16x32_bf16 v[58:61], v[168:171], v[192:195], v[58:61]
	v_mfma_f32_16x16x32_bf16 v[54:57], v[160:163], v[200:203], v[54:57]
	v_mfma_f32_16x16x32_bf16 v[46:49], v[168:171], v[200:203], v[46:49]
	v_mfma_f32_16x16x32_bf16 v[38:41], v[160:163], v[208:211], v[38:41]
	v_mfma_f32_16x16x32_bf16 v[30:33], v[168:171], v[208:211], v[30:33]
	v_mfma_f32_16x16x32_bf16 v[22:25], v[160:163], v[216:219], v[22:25]
	v_mfma_f32_16x16x32_bf16 v[14:17], v[168:171], v[216:219], v[14:17]
	s_setprio 1
	s_setprio 0
	v_mfma_f32_16x16x32_bf16 v[50:53], v[172:175], v[188:191], v[50:53]
	v_mfma_f32_16x16x32_bf16 v[42:45], v[180:183], v[188:191], v[42:45]
	v_mfma_f32_16x16x32_bf16 v[34:37], v[172:175], v[196:199], v[34:37]
	v_mfma_f32_16x16x32_bf16 v[26:29], v[180:183], v[196:199], v[26:29]
	v_mfma_f32_16x16x32_bf16 v[18:21], v[172:175], v[204:207], v[18:21]
	v_mfma_f32_16x16x32_bf16 v[10:13], v[180:183], v[204:207], v[10:13]
	v_mfma_f32_16x16x32_bf16 v[6:9], v[172:175], v[212:215], v[6:9]
	v_mfma_f32_16x16x32_bf16 v[2:5], v[180:183], v[212:215], v[2:5]
	v_mfma_f32_16x16x32_bf16 v[50:53], v[176:179], v[192:195], v[50:53]
	v_mfma_f32_16x16x32_bf16 v[42:45], v[184:187], v[192:195], v[42:45]
	v_mfma_f32_16x16x32_bf16 v[34:37], v[176:179], v[200:203], v[34:37]
	v_mfma_f32_16x16x32_bf16 v[26:29], v[184:187], v[200:203], v[26:29]
	v_mfma_f32_16x16x32_bf16 v[18:21], v[176:179], v[208:211], v[18:21]
	v_mfma_f32_16x16x32_bf16 v[10:13], v[184:187], v[208:211], v[10:13]
	v_mfma_f32_16x16x32_bf16 v[6:9], v[176:179], v[216:219], v[6:9]
	v_mfma_f32_16x16x32_bf16 v[2:5], v[184:187], v[216:219], v[2:5]
	s_setprio 1
	s_barrier
	s_add_i32 s56, 0, 0x18000
	s_add_i32 s57, 0, 0x1c000
	v_add_u32_e32 v168, s56, v150
	v_add_u32_e32 v184, s57, v150
	ds_read_b128 v[156:159], v168
	ds_read_b128 v[160:163], v168 offset:1024
	ds_read_b128 v[164:167], v168 offset:2048
	ds_read_b128 v[168:171], v168 offset:3072
	ds_read_b128 v[172:175], v184
	ds_read_b128 v[176:179], v184 offset:1024
	ds_read_b128 v[180:183], v184 offset:2048
	ds_read_b128 v[184:187], v184 offset:3072
	s_add_u32 s28, s28, 0x80000
	s_addc_u32 s29, s29, 0
	s_mov_b32 m0, s40
	v_lshl_add_u64 v[228:229], s[28:29], 0, v[136:137]
	ds_read_b128 v[188:191], v155 offset:32768
	ds_read_b128 v[192:195], v155 offset:33792
	ds_read_b128 v[196:199], v155 offset:34816
	ds_read_b128 v[200:203], v155 offset:35840
	ds_read_b128 v[204:207], v155 offset:36864
	ds_read_b128 v[208:211], v155 offset:37888
	ds_read_b128 v[212:215], v155 offset:38912
	ds_read_b128 v[216:219], v155 offset:39936
	global_load_lds_dwordx4 v[228:229], off
	v_lshl_add_u64 v[228:229], s[28:29], 0, v[132:133]
	s_mov_b32 m0, s41
	s_nop 0
	global_load_lds_dwordx4 v[228:229], off
	s_waitcnt vmcnt(8)
	s_waitcnt lgkmcnt(0)
	s_barrier
	s_setprio 0
	s_waitcnt lgkmcnt(0)
	v_mfma_f32_16x16x32_bf16 v[126:129], v[156:159], v[188:191], v[126:129]
	v_mfma_f32_16x16x32_bf16 v[122:125], v[164:167], v[188:191], v[122:125]
	v_mfma_f32_16x16x32_bf16 v[118:121], v[156:159], v[196:199], v[118:121]
	v_mfma_f32_16x16x32_bf16 v[110:113], v[164:167], v[196:199], v[110:113]
	v_mfma_f32_16x16x32_bf16 v[102:105], v[156:159], v[204:207], v[102:105]
	v_mfma_f32_16x16x32_bf16 v[94:97], v[164:167], v[204:207], v[94:97]
	v_mfma_f32_16x16x32_bf16 v[86:89], v[156:159], v[212:215], v[86:89]
	v_mfma_f32_16x16x32_bf16 v[78:81], v[164:167], v[212:215], v[78:81]
	v_mfma_f32_16x16x32_bf16 v[126:129], v[160:163], v[192:195], v[126:129]
	v_mfma_f32_16x16x32_bf16 v[122:125], v[168:171], v[192:195], v[122:125]
	v_mfma_f32_16x16x32_bf16 v[118:121], v[160:163], v[200:203], v[118:121]
	v_mfma_f32_16x16x32_bf16 v[110:113], v[168:171], v[200:203], v[110:113]
	v_mfma_f32_16x16x32_bf16 v[102:105], v[160:163], v[208:211], v[102:105]
	v_mfma_f32_16x16x32_bf16 v[94:97], v[168:171], v[208:211], v[94:97]
	v_mfma_f32_16x16x32_bf16 v[86:89], v[160:163], v[216:219], v[86:89]
	v_mfma_f32_16x16x32_bf16 v[78:81], v[168:171], v[216:219], v[78:81]
	s_setprio 1
	s_setprio 0
	v_mfma_f32_16x16x32_bf16 v[114:117], v[172:175], v[188:191], v[114:117]
	v_mfma_f32_16x16x32_bf16 v[106:109], v[180:183], v[188:191], v[106:109]
	v_mfma_f32_16x16x32_bf16 v[98:101], v[172:175], v[196:199], v[98:101]
	v_mfma_f32_16x16x32_bf16 v[90:93], v[180:183], v[196:199], v[90:93]
	v_mfma_f32_16x16x32_bf16 v[82:85], v[172:175], v[204:207], v[82:85]
	v_mfma_f32_16x16x32_bf16 v[74:77], v[180:183], v[204:207], v[74:77]
	v_mfma_f32_16x16x32_bf16 v[70:73], v[172:175], v[212:215], v[70:73]
	v_mfma_f32_16x16x32_bf16 v[66:69], v[180:183], v[212:215], v[66:69]
	v_mfma_f32_16x16x32_bf16 v[114:117], v[176:179], v[192:195], v[114:117]
	v_mfma_f32_16x16x32_bf16 v[106:109], v[184:187], v[192:195], v[106:109]
	v_mfma_f32_16x16x32_bf16 v[98:101], v[176:179], v[200:203], v[98:101]
	v_mfma_f32_16x16x32_bf16 v[90:93], v[184:187], v[200:203], v[90:93]
	v_mfma_f32_16x16x32_bf16 v[82:85], v[176:179], v[208:211], v[82:85]
	v_mfma_f32_16x16x32_bf16 v[74:77], v[184:187], v[208:211], v[74:77]
	v_mfma_f32_16x16x32_bf16 v[70:73], v[176:179], v[216:219], v[70:73]
	v_mfma_f32_16x16x32_bf16 v[66:69], v[184:187], v[216:219], v[66:69]
	s_setprio 1
	s_barrier
	s_add_i32 s28, s56, s36
	v_lshl_add_u64 v[220:221], v[220:221], 0, s[6:7]
	s_mov_b32 m0, s28
	ds_read_b128 v[188:191], v155 offset:49152
	ds_read_b128 v[192:195], v155 offset:50176
	ds_read_b128 v[196:199], v155 offset:51200
	ds_read_b128 v[200:203], v155 offset:52224
	ds_read_b128 v[204:207], v155 offset:53248
	ds_read_b128 v[208:211], v155 offset:54272
	ds_read_b128 v[212:215], v155 offset:55296
	ds_read_b128 v[216:219], v155 offset:56320
	global_load_lds_dwordx4 v[220:221], off
	s_add_i32 m0, s28, 0x2000
	s_add_u32 s26, s26, 0x80080
	v_lshl_add_u64 v[220:221], v[222:223], 0, s[6:7]
	s_addc_u32 s27, s27, 0
	s_add_i32 s28, s57, s36
	global_load_lds_dwordx4 v[220:221], off
	v_lshl_add_u64 v[220:221], s[26:27], 0, v[134:135]
	s_mov_b32 m0, s28
	s_nop 0
	global_load_lds_dwordx4 v[220:221], off
	v_lshl_add_u64 v[220:221], s[26:27], 0, v[130:131]
	s_add_i32 m0, s28, 0x2000
	s_nop 0
	global_load_lds_dwordx4 v[220:221], off
	v_lshl_add_u64 v[220:221], v[224:225], 0, s[6:7]
	s_mov_b32 m0, s42
	s_nop 0
	global_load_lds_dwordx4 v[220:221], off
	v_lshl_add_u64 v[220:221], v[226:227], 0, s[6:7]
	s_mov_b32 m0, s43
	s_nop 0
	global_load_lds_dwordx4 v[220:221], off
	s_waitcnt vmcnt(8)
	s_waitcnt lgkmcnt(0)
	s_barrier
	s_setprio 0
	s_waitcnt lgkmcnt(0)
	v_mfma_f32_16x16x32_bf16 v[62:65], v[156:159], v[188:191], v[62:65]
	v_mfma_f32_16x16x32_bf16 v[58:61], v[164:167], v[188:191], v[58:61]
	v_mfma_f32_16x16x32_bf16 v[54:57], v[156:159], v[196:199], v[54:57]
	v_mfma_f32_16x16x32_bf16 v[46:49], v[164:167], v[196:199], v[46:49]
	v_mfma_f32_16x16x32_bf16 v[38:41], v[156:159], v[204:207], v[38:41]
	v_mfma_f32_16x16x32_bf16 v[30:33], v[164:167], v[204:207], v[30:33]
	v_mfma_f32_16x16x32_bf16 v[22:25], v[156:159], v[212:215], v[22:25]
	v_mfma_f32_16x16x32_bf16 v[14:17], v[164:167], v[212:215], v[14:17]
	v_mfma_f32_16x16x32_bf16 v[62:65], v[160:163], v[192:195], v[62:65]
	v_mfma_f32_16x16x32_bf16 v[58:61], v[168:171], v[192:195], v[58:61]
	v_mfma_f32_16x16x32_bf16 v[54:57], v[160:163], v[200:203], v[54:57]
	v_mfma_f32_16x16x32_bf16 v[46:49], v[168:171], v[200:203], v[46:49]
	v_mfma_f32_16x16x32_bf16 v[38:41], v[160:163], v[208:211], v[38:41]
	v_mfma_f32_16x16x32_bf16 v[30:33], v[168:171], v[208:211], v[30:33]
	v_mfma_f32_16x16x32_bf16 v[22:25], v[160:163], v[216:219], v[22:25]
	v_mfma_f32_16x16x32_bf16 v[14:17], v[168:171], v[216:219], v[14:17]
	s_setprio 1
	s_setprio 0
	v_mfma_f32_16x16x32_bf16 v[50:53], v[172:175], v[188:191], v[50:53]
	v_mfma_f32_16x16x32_bf16 v[42:45], v[180:183], v[188:191], v[42:45]
	v_mfma_f32_16x16x32_bf16 v[34:37], v[172:175], v[196:199], v[34:37]
	v_mfma_f32_16x16x32_bf16 v[26:29], v[180:183], v[196:199], v[26:29]
	v_mfma_f32_16x16x32_bf16 v[18:21], v[172:175], v[204:207], v[18:21]
	v_mfma_f32_16x16x32_bf16 v[10:13], v[180:183], v[204:207], v[10:13]
	v_mfma_f32_16x16x32_bf16 v[6:9], v[172:175], v[212:215], v[6:9]
	v_mfma_f32_16x16x32_bf16 v[2:5], v[180:183], v[212:215], v[2:5]
	v_mfma_f32_16x16x32_bf16 v[50:53], v[176:179], v[192:195], v[50:53]
	v_mfma_f32_16x16x32_bf16 v[42:45], v[184:187], v[192:195], v[42:45]
	v_mfma_f32_16x16x32_bf16 v[34:37], v[176:179], v[200:203], v[34:37]
	v_mfma_f32_16x16x32_bf16 v[26:29], v[184:187], v[200:203], v[26:29]
	v_mfma_f32_16x16x32_bf16 v[18:21], v[176:179], v[208:211], v[18:21]
	v_mfma_f32_16x16x32_bf16 v[10:13], v[184:187], v[208:211], v[10:13]
	v_mfma_f32_16x16x32_bf16 v[6:9], v[176:179], v[216:219], v[6:9]
	v_mfma_f32_16x16x32_bf16 v[2:5], v[184:187], v[216:219], v[2:5]
	s_setprio 1
	s_barrier
	s_add_i32 s55, s55, 2
	s_add_u32 s24, s24, 0x100
	s_addc_u32 s25, s25, 0
	s_cmp_gt_u32 s55, 29
	s_cbranch_scc0 .LBB0_1173
	s_and_b64 vcc, exec, s[8:9]
	s_cbranch_vccz .LBB0_1176
	s_barrier

.Lwe_10:
	s_waitcnt lgkmcnt(0)
	s_barrier
	s_setprio 0
	s_waitcnt lgkmcnt(0)
	v_mfma_f32_16x16x32_bf16 v[126:129], v[156:159], v[188:191], v[126:129]
	v_mfma_f32_16x16x32_bf16 v[122:125], v[164:167], v[188:191], v[122:125]
	v_mfma_f32_16x16x32_bf16 v[118:121], v[156:159], v[196:199], v[118:121]
	v_mfma_f32_16x16x32_bf16 v[110:113], v[164:167], v[196:199], v[110:113]
	v_mfma_f32_16x16x32_bf16 v[102:105], v[156:159], v[204:207], v[102:105]
	v_mfma_f32_16x16x32_bf16 v[94:97], v[164:167], v[204:207], v[94:97]
	v_mfma_f32_16x16x32_bf16 v[86:89], v[156:159], v[212:215], v[86:89]
	v_mfma_f32_16x16x32_bf16 v[78:81], v[164:167], v[212:215], v[78:81]
	v_mfma_f32_16x16x32_bf16 v[126:129], v[160:163], v[192:195], v[126:129]
	v_mfma_f32_16x16x32_bf16 v[122:125], v[168:171], v[192:195], v[122:125]
	v_mfma_f32_16x16x32_bf16 v[118:121], v[160:163], v[200:203], v[118:121]
	v_mfma_f32_16x16x32_bf16 v[110:113], v[168:171], v[200:203], v[110:113]
	v_mfma_f32_16x16x32_bf16 v[102:105], v[160:163], v[208:211], v[102:105]
	v_mfma_f32_16x16x32_bf16 v[94:97], v[168:171], v[208:211], v[94:97]
	v_mfma_f32_16x16x32_bf16 v[86:89], v[160:163], v[216:219], v[86:89]
	v_mfma_f32_16x16x32_bf16 v[78:81], v[168:171], v[216:219], v[78:81]
	s_setprio 1
	s_setprio 0
	v_mfma_f32_16x16x32_bf16 v[114:117], v[172:175], v[188:191], v[114:117]
	v_mfma_f32_16x16x32_bf16 v[106:109], v[180:183], v[188:191], v[106:109]
	v_mfma_f32_16x16x32_bf16 v[98:101], v[172:175], v[196:199], v[98:101]
	v_mfma_f32_16x16x32_bf16 v[90:93], v[180:183], v[196:199], v[90:93]
	v_mfma_f32_16x16x32_bf16 v[82:85], v[172:175], v[204:207], v[82:85]
	v_mfma_f32_16x16x32_bf16 v[74:77], v[180:183], v[204:207], v[74:77]
	v_mfma_f32_16x16x32_bf16 v[70:73], v[172:175], v[212:215], v[70:73]
	v_mfma_f32_16x16x32_bf16 v[66:69], v[180:183], v[212:215], v[66:69]
	v_mfma_f32_16x16x32_bf16 v[114:117], v[176:179], v[192:195], v[114:117]
	v_mfma_f32_16x16x32_bf16 v[106:109], v[184:187], v[192:195], v[106:109]
	v_mfma_f32_16x16x32_bf16 v[98:101], v[176:179], v[200:203], v[98:101]
	v_mfma_f32_16x16x32_bf16 v[90:93], v[184:187], v[200:203], v[90:93]
	v_mfma_f32_16x16x32_bf16 v[82:85], v[176:179], v[208:211], v[82:85]
	v_mfma_f32_16x16x32_bf16 v[74:77], v[184:187], v[208:211], v[74:77]
	v_mfma_f32_16x16x32_bf16 v[70:73], v[176:179], v[216:219], v[70:73]
	v_mfma_f32_16x16x32_bf16 v[66:69], v[184:187], v[216:219], v[66:69]
	s_setprio 1
	s_barrier
	s_add_i32 s62, s48, s39
	v_lshl_add_u64 v[220:221], s[28:29], 0, v[132:133]
	s_mov_b32 m0, s62
	ds_read_b128 v[188:191], v155 offset:16384
	ds_read_b128 v[192:195], v155 offset:17408
	ds_read_b128 v[196:199], v155 offset:18432
	ds_read_b128 v[200:203], v155 offset:19456
	ds_read_b128 v[204:207], v155 offset:20480
	ds_read_b128 v[208:211], v155 offset:21504
	ds_read_b128 v[212:215], v155 offset:22528
	ds_read_b128 v[216:219], v155 offset:23552
	global_load_lds_dwordx4 v[220:221], off
	s_add_i32 m0, s62, 0x2000
	s_add_u32 s62, s28, 0x160000
	v_lshl_add_u64 v[222:223], s[28:29], 0, v[136:137]
	s_addc_u32 s63, s29, 0
	s_add_i32 s65, s49, s39
	global_load_lds_dwordx4 v[222:223], off
	v_lshl_add_u64 v[224:225], s[62:63], 0, v[132:133]
	s_mov_b32 m0, s65
	v_lshl_add_u64 v[226:227], s[30:31], 0, v[134:135]
	global_load_lds_dwordx4 v[224:225], off
	v_lshl_add_u64 v[224:225], s[62:63], 0, v[136:137]
	s_add_i32 m0, s65, 0x2000
	s_nop 0
	global_load_lds_dwordx4 v[224:225], off
	v_lshl_add_u64 v[224:225], s[30:31], 0, v[130:131]
	s_mov_b32 m0, s40
	s_nop 0
	global_load_lds_dwordx4 v[224:225], off
	s_mov_b32 m0, s41
	s_nop 0
	global_load_lds_dwordx4 v[226:227], off
	s_cmp_eq_u32 s64, 0
	s_cbranch_scc1 .Lw8_11
	s_waitcnt vmcnt(24)
	s_branch .Lwe_11

.Lwe_11:
	s_waitcnt lgkmcnt(0)
	s_barrier
	s_setprio 0
	s_waitcnt lgkmcnt(0)
	v_mfma_f32_16x16x32_bf16 v[62:65], v[156:159], v[188:191], v[62:65]
	v_mfma_f32_16x16x32_bf16 v[58:61], v[164:167], v[188:191], v[58:61]
	v_mfma_f32_16x16x32_bf16 v[54:57], v[156:159], v[196:199], v[54:57]
	v_mfma_f32_16x16x32_bf16 v[46:49], v[164:167], v[196:199], v[46:49]
	v_mfma_f32_16x16x32_bf16 v[38:41], v[156:159], v[204:207], v[38:41]
	v_mfma_f32_16x16x32_bf16 v[30:33], v[164:167], v[204:207], v[30:33]
	v_mfma_f32_16x16x32_bf16 v[22:25], v[156:159], v[212:215], v[22:25]
	v_mfma_f32_16x16x32_bf16 v[14:17], v[164:167], v[212:215], v[14:17]
	v_mfma_f32_16x16x32_bf16 v[62:65], v[160:163], v[192:195], v[62:65]
	v_mfma_f32_16x16x32_bf16 v[58:61], v[168:171], v[192:195], v[58:61]
	v_mfma_f32_16x16x32_bf16 v[54:57], v[160:163], v[200:203], v[54:57]
	v_mfma_f32_16x16x32_bf16 v[46:49], v[168:171], v[200:203], v[46:49]
	v_mfma_f32_16x16x32_bf16 v[38:41], v[160:163], v[208:211], v[38:41]
	v_mfma_f32_16x16x32_bf16 v[30:33], v[168:171], v[208:211], v[30:33]
	v_mfma_f32_16x16x32_bf16 v[22:25], v[160:163], v[216:219], v[22:25]
	v_mfma_f32_16x16x32_bf16 v[14:17], v[168:171], v[216:219], v[14:17]
	s_setprio 1
	s_setprio 0
	v_mfma_f32_16x16x32_bf16 v[50:53], v[172:175], v[188:191], v[50:53]
	v_mfma_f32_16x16x32_bf16 v[42:45], v[180:183], v[188:191], v[42:45]
	v_mfma_f32_16x16x32_bf16 v[34:37], v[172:175], v[196:199], v[34:37]
	v_mfma_f32_16x16x32_bf16 v[26:29], v[180:183], v[196:199], v[26:29]
	v_mfma_f32_16x16x32_bf16 v[18:21], v[172:175], v[204:207], v[18:21]
	v_mfma_f32_16x16x32_bf16 v[10:13], v[180:183], v[204:207], v[10:13]
	v_mfma_f32_16x16x32_bf16 v[6:9], v[172:175], v[212:215], v[6:9]
	v_mfma_f32_16x16x32_bf16 v[2:5], v[180:183], v[212:215], v[2:5]
	v_mfma_f32_16x16x32_bf16 v[50:53], v[176:179], v[192:195], v[50:53]
	v_mfma_f32_16x16x32_bf16 v[42:45], v[184:187], v[192:195], v[42:45]
	v_mfma_f32_16x16x32_bf16 v[34:37], v[176:179], v[200:203], v[34:37]
	v_mfma_f32_16x16x32_bf16 v[26:29], v[184:187], v[200:203], v[26:29]
	v_mfma_f32_16x16x32_bf16 v[18:21], v[176:179], v[208:211], v[18:21]
	v_mfma_f32_16x16x32_bf16 v[10:13], v[184:187], v[208:211], v[10:13]
	v_mfma_f32_16x16x32_bf16 v[6:9], v[176:179], v[216:219], v[6:9]
	v_mfma_f32_16x16x32_bf16 v[2:5], v[184:187], v[216:219], v[2:5]
	s_setprio 1
	s_barrier
	s_add_i32 s62, 0, 0x18000
	s_add_i32 s63, 0, 0x1c000
	v_add_u32_e32 v168, s62, v150
	v_add_u32_e32 v184, s63, v150
	ds_read_b128 v[156:159], v168
	ds_read_b128 v[160:163], v168 offset:1024
	ds_read_b128 v[164:167], v168 offset:2048
	ds_read_b128 v[168:171], v168 offset:3072
	ds_read_b128 v[172:175], v184
	ds_read_b128 v[176:179], v184 offset:1024
	ds_read_b128 v[180:183], v184 offset:2048
	ds_read_b128 v[184:187], v184 offset:3072
	s_add_u32 s30, s30, 0x160000
	s_addc_u32 s31, s31, 0
	s_mov_b32 m0, s42
	v_lshl_add_u64 v[228:229], s[30:31], 0, v[130:131]
	ds_read_b128 v[188:191], v155 offset:32768
	ds_read_b128 v[192:195], v155 offset:33792
	ds_read_b128 v[196:199], v155 offset:34816
	ds_read_b128 v[200:203], v155 offset:35840
	ds_read_b128 v[204:207], v155 offset:36864
	ds_read_b128 v[208:211], v155 offset:37888
	ds_read_b128 v[212:215], v155 offset:38912
	ds_read_b128 v[216:219], v155 offset:39936
	global_load_lds_dwordx4 v[228:229], off
	v_lshl_add_u64 v[228:229], s[30:31], 0, v[134:135]
	s_mov_b32 m0, s43
	s_nop 0
	global_load_lds_dwordx4 v[228:229], off
	s_waitcnt vmcnt(8)
	s_waitcnt lgkmcnt(0)
	s_barrier
	s_setprio 0
	s_waitcnt lgkmcnt(0)
	v_mfma_f32_16x16x32_bf16 v[126:129], v[156:159], v[188:191], v[126:129]
	v_mfma_f32_16x16x32_bf16 v[122:125], v[164:167], v[188:191], v[122:125]
	v_mfma_f32_16x16x32_bf16 v[118:121], v[156:159], v[196:199], v[118:121]
	v_mfma_f32_16x16x32_bf16 v[110:113], v[164:167], v[196:199], v[110:113]
	v_mfma_f32_16x16x32_bf16 v[102:105], v[156:159], v[204:207], v[102:105]
	v_mfma_f32_16x16x32_bf16 v[94:97], v[164:167], v[204:207], v[94:97]
	v_mfma_f32_16x16x32_bf16 v[86:89], v[156:159], v[212:215], v[86:89]
	v_mfma_f32_16x16x32_bf16 v[78:81], v[164:167], v[212:215], v[78:81]
	v_mfma_f32_16x16x32_bf16 v[126:129], v[160:163], v[192:195], v[126:129]
	v_mfma_f32_16x16x32_bf16 v[122:125], v[168:171], v[192:195], v[122:125]
	v_mfma_f32_16x16x32_bf16 v[118:121], v[160:163], v[200:203], v[118:121]
	v_mfma_f32_16x16x32_bf16 v[110:113], v[168:171], v[200:203], v[110:113]
	v_mfma_f32_16x16x32_bf16 v[102:105], v[160:163], v[208:211], v[102:105]
	v_mfma_f32_16x16x32_bf16 v[94:97], v[168:171], v[208:211], v[94:97]
	v_mfma_f32_16x16x32_bf16 v[86:89], v[160:163], v[216:219], v[86:89]
	v_mfma_f32_16x16x32_bf16 v[78:81], v[168:171], v[216:219], v[78:81]
	s_setprio 1
	s_setprio 0
	v_mfma_f32_16x16x32_bf16 v[114:117], v[172:175], v[188:191], v[114:117]
	v_mfma_f32_16x16x32_bf16 v[106:109], v[180:183], v[188:191], v[106:109]
	v_mfma_f32_16x16x32_bf16 v[98:101], v[172:175], v[196:199], v[98:101]
	v_mfma_f32_16x16x32_bf16 v[90:93], v[180:183], v[196:199], v[90:93]
	v_mfma_f32_16x16x32_bf16 v[82:85], v[172:175], v[204:207], v[82:85]
	v_mfma_f32_16x16x32_bf16 v[74:77], v[180:183], v[204:207], v[74:77]
	v_mfma_f32_16x16x32_bf16 v[70:73], v[172:175], v[212:215], v[70:73]
	v_mfma_f32_16x16x32_bf16 v[66:69], v[180:183], v[212:215], v[66:69]
	v_mfma_f32_16x16x32_bf16 v[114:117], v[176:179], v[192:195], v[114:117]
	v_mfma_f32_16x16x32_bf16 v[106:109], v[184:187], v[192:195], v[106:109]
	v_mfma_f32_16x16x32_bf16 v[98:101], v[176:179], v[200:203], v[98:101]
	v_mfma_f32_16x16x32_bf16 v[90:93], v[184:187], v[200:203], v[90:93]
	v_mfma_f32_16x16x32_bf16 v[82:85], v[176:179], v[208:211], v[82:85]
	v_mfma_f32_16x16x32_bf16 v[74:77], v[184:187], v[208:211], v[74:77]
	v_mfma_f32_16x16x32_bf16 v[70:73], v[176:179], v[216:219], v[70:73]
	v_mfma_f32_16x16x32_bf16 v[66:69], v[184:187], v[216:219], v[66:69]
	s_setprio 1
	s_barrier
	s_add_i32 s30, s62, s39
	v_lshl_add_u64 v[220:221], v[220:221], 0, s[8:9]
	s_mov_b32 m0, s30
	ds_read_b128 v[188:191], v155 offset:49152
	ds_read_b128 v[192:195], v155 offset:50176
	ds_read_b128 v[196:199], v155 offset:51200
	ds_read_b128 v[200:203], v155 offset:52224
	ds_read_b128 v[204:207], v155 offset:53248
	ds_read_b128 v[208:211], v155 offset:54272
	ds_read_b128 v[212:215], v155 offset:55296
	ds_read_b128 v[216:219], v155 offset:56320
	global_load_lds_dwordx4 v[220:221], off
	s_add_i32 m0, s30, 0x2000
	s_add_u32 s28, s28, 0x160080
	v_lshl_add_u64 v[220:221], v[222:223], 0, s[8:9]
	s_addc_u32 s29, s29, 0
	s_add_i32 s30, s63, s39
	global_load_lds_dwordx4 v[220:221], off
	v_lshl_add_u64 v[220:221], s[28:29], 0, v[132:133]
	s_mov_b32 m0, s30
	s_nop 0
	global_load_lds_dwordx4 v[220:221], off
	v_lshl_add_u64 v[220:221], s[28:29], 0, v[136:137]
	s_add_i32 m0, s30, 0x2000
	s_nop 0
	global_load_lds_dwordx4 v[220:221], off
	v_lshl_add_u64 v[220:221], v[224:225], 0, s[8:9]
	s_mov_b32 m0, s44
	s_nop 0
	global_load_lds_dwordx4 v[220:221], off
	v_lshl_add_u64 v[220:221], v[226:227], 0, s[8:9]
	s_mov_b32 m0, s45
	s_nop 0
	global_load_lds_dwordx4 v[220:221], off
	s_waitcnt vmcnt(8)
	s_waitcnt lgkmcnt(0)
	s_barrier
	s_setprio 0
	s_waitcnt lgkmcnt(0)
	v_mfma_f32_16x16x32_bf16 v[62:65], v[156:159], v[188:191], v[62:65]
	v_mfma_f32_16x16x32_bf16 v[58:61], v[164:167], v[188:191], v[58:61]
	v_mfma_f32_16x16x32_bf16 v[54:57], v[156:159], v[196:199], v[54:57]
	v_mfma_f32_16x16x32_bf16 v[46:49], v[164:167], v[196:199], v[46:49]
	v_mfma_f32_16x16x32_bf16 v[38:41], v[156:159], v[204:207], v[38:41]
	v_mfma_f32_16x16x32_bf16 v[30:33], v[164:167], v[204:207], v[30:33]
	v_mfma_f32_16x16x32_bf16 v[22:25], v[156:159], v[212:215], v[22:25]
	v_mfma_f32_16x16x32_bf16 v[14:17], v[164:167], v[212:215], v[14:17]
	v_mfma_f32_16x16x32_bf16 v[62:65], v[160:163], v[192:195], v[62:65]
	v_mfma_f32_16x16x32_bf16 v[58:61], v[168:171], v[192:195], v[58:61]
	v_mfma_f32_16x16x32_bf16 v[54:57], v[160:163], v[200:203], v[54:57]
	v_mfma_f32_16x16x32_bf16 v[46:49], v[168:171], v[200:203], v[46:49]
	v_mfma_f32_16x16x32_bf16 v[38:41], v[160:163], v[208:211], v[38:41]
	v_mfma_f32_16x16x32_bf16 v[30:33], v[168:171], v[208:211], v[30:33]
	v_mfma_f32_16x16x32_bf16 v[22:25], v[160:163], v[216:219], v[22:25]
	v_mfma_f32_16x16x32_bf16 v[14:17], v[168:171], v[216:219], v[14:17]
	s_setprio 1
	s_setprio 0
	v_mfma_f32_16x16x32_bf16 v[50:53], v[172:175], v[188:191], v[50:53]
	v_mfma_f32_16x16x32_bf16 v[42:45], v[180:183], v[188:191], v[42:45]
	v_mfma_f32_16x16x32_bf16 v[34:37], v[172:175], v[196:199], v[34:37]
	v_mfma_f32_16x16x32_bf16 v[26:29], v[180:183], v[196:199], v[26:29]
	v_mfma_f32_16x16x32_bf16 v[18:21], v[172:175], v[204:207], v[18:21]
	v_mfma_f32_16x16x32_bf16 v[10:13], v[180:183], v[204:207], v[10:13]
	v_mfma_f32_16x16x32_bf16 v[6:9], v[172:175], v[212:215], v[6:9]
	v_mfma_f32_16x16x32_bf16 v[2:5], v[180:183], v[212:215], v[2:5]
	v_mfma_f32_16x16x32_bf16 v[50:53], v[176:179], v[192:195], v[50:53]
	v_mfma_f32_16x16x32_bf16 v[42:45], v[184:187], v[192:195], v[42:45]
	v_mfma_f32_16x16x32_bf16 v[34:37], v[176:179], v[200:203], v[34:37]
	v_mfma_f32_16x16x32_bf16 v[26:29], v[184:187], v[200:203], v[26:29]
	v_mfma_f32_16x16x32_bf16 v[18:21], v[176:179], v[208:211], v[18:21]
	v_mfma_f32_16x16x32_bf16 v[10:13], v[184:187], v[208:211], v[10:13]
	v_mfma_f32_16x16x32_bf16 v[6:9], v[176:179], v[216:219], v[6:9]
	v_mfma_f32_16x16x32_bf16 v[2:5], v[184:187], v[216:219], v[2:5]
	s_setprio 1
	s_barrier
	s_add_i32 s61, s61, 2
	s_add_u32 s26, s26, 0x100
	s_addc_u32 s27, s27, 0
	s_cmpk_gt_u32 s61, 0x55
	s_cbranch_scc0 .LBB0_1417
	s_and_b64 vcc, exec, s[10:11]
	s_cbranch_vccz .LBB0_1420
	s_barrier

.Lwe_12:
	s_waitcnt lgkmcnt(0)
	s_barrier
	s_setprio 0
	s_waitcnt lgkmcnt(0)
	v_mfma_f32_16x16x32_bf16 v[126:129], v[158:161], v[190:193], v[126:129]
	v_mfma_f32_16x16x32_bf16 v[122:125], v[166:169], v[190:193], v[122:125]
	v_mfma_f32_16x16x32_bf16 v[118:121], v[158:161], v[198:201], v[118:121]
	v_mfma_f32_16x16x32_bf16 v[110:113], v[166:169], v[198:201], v[110:113]
	v_mfma_f32_16x16x32_bf16 v[102:105], v[158:161], v[206:209], v[102:105]
	v_mfma_f32_16x16x32_bf16 v[94:97], v[166:169], v[206:209], v[94:97]
	v_mfma_f32_16x16x32_bf16 v[86:89], v[158:161], v[214:217], v[86:89]
	v_mfma_f32_16x16x32_bf16 v[78:81], v[166:169], v[214:217], v[78:81]
	v_mfma_f32_16x16x32_bf16 v[126:129], v[162:165], v[194:197], v[126:129]
	v_mfma_f32_16x16x32_bf16 v[122:125], v[170:173], v[194:197], v[122:125]
	v_mfma_f32_16x16x32_bf16 v[118:121], v[162:165], v[202:205], v[118:121]
	v_mfma_f32_16x16x32_bf16 v[110:113], v[170:173], v[202:205], v[110:113]
	v_mfma_f32_16x16x32_bf16 v[102:105], v[162:165], v[210:213], v[102:105]
	v_mfma_f32_16x16x32_bf16 v[94:97], v[170:173], v[210:213], v[94:97]
	v_mfma_f32_16x16x32_bf16 v[86:89], v[162:165], v[218:221], v[86:89]
	v_mfma_f32_16x16x32_bf16 v[78:81], v[170:173], v[218:221], v[78:81]
	s_setprio 1
	s_setprio 0
	v_mfma_f32_16x16x32_bf16 v[114:117], v[174:177], v[190:193], v[114:117]
	v_mfma_f32_16x16x32_bf16 v[106:109], v[182:185], v[190:193], v[106:109]
	v_mfma_f32_16x16x32_bf16 v[98:101], v[174:177], v[198:201], v[98:101]
	v_mfma_f32_16x16x32_bf16 v[90:93], v[182:185], v[198:201], v[90:93]
	v_mfma_f32_16x16x32_bf16 v[82:85], v[174:177], v[206:209], v[82:85]
	v_mfma_f32_16x16x32_bf16 v[74:77], v[182:185], v[206:209], v[74:77]
	v_mfma_f32_16x16x32_bf16 v[70:73], v[174:177], v[214:217], v[70:73]
	v_mfma_f32_16x16x32_bf16 v[66:69], v[182:185], v[214:217], v[66:69]
	v_mfma_f32_16x16x32_bf16 v[114:117], v[178:181], v[194:197], v[114:117]
	v_mfma_f32_16x16x32_bf16 v[106:109], v[186:189], v[194:197], v[106:109]
	v_mfma_f32_16x16x32_bf16 v[98:101], v[178:181], v[202:205], v[98:101]
	v_mfma_f32_16x16x32_bf16 v[90:93], v[186:189], v[202:205], v[90:93]
	v_mfma_f32_16x16x32_bf16 v[82:85], v[178:181], v[210:213], v[82:85]
	v_mfma_f32_16x16x32_bf16 v[74:77], v[186:189], v[210:213], v[74:77]
	v_mfma_f32_16x16x32_bf16 v[70:73], v[178:181], v[218:221], v[70:73]
	v_mfma_f32_16x16x32_bf16 v[66:69], v[186:189], v[218:221], v[66:69]
	s_setprio 1
	s_barrier
	s_add_i32 s70, s60, s48
	v_lshl_add_u64 v[222:223], s[40:41], 0, v[134:135]
	s_mov_b32 m0, s70
	ds_read_b128 v[190:193], v156 offset:16384
	ds_read_b128 v[194:197], v156 offset:17408
	ds_read_b128 v[198:201], v156 offset:18432
	ds_read_b128 v[202:205], v156 offset:19456
	ds_read_b128 v[206:209], v156 offset:20480
	ds_read_b128 v[210:213], v156 offset:21504
	ds_read_b128 v[214:217], v156 offset:22528
	ds_read_b128 v[218:221], v156 offset:23552
	global_load_lds_dwordx4 v[222:223], off
	s_add_i32 m0, s70, 0x2000
	s_add_u32 s70, s40, 0x80000
	v_lshl_add_u64 v[224:225], s[40:41], 0, v[130:131]
	s_addc_u32 s71, s41, 0
	s_add_i32 s73, s61, s48
	global_load_lds_dwordx4 v[224:225], off
	v_lshl_add_u64 v[226:227], s[70:71], 0, v[134:135]
	s_mov_b32 m0, s73
	v_lshl_add_u64 v[228:229], s[42:43], 0, v[132:133]
	global_load_lds_dwordx4 v[226:227], off
	v_lshl_add_u64 v[226:227], s[70:71], 0, v[130:131]
	s_add_i32 m0, s73, 0x2000
	s_nop 0
	global_load_lds_dwordx4 v[226:227], off
	v_lshl_add_u64 v[226:227], s[42:43], 0, v[136:137]
	s_mov_b32 m0, s51
	s_nop 0
	global_load_lds_dwordx4 v[226:227], off
	s_mov_b32 m0, s52
	s_nop 0
	global_load_lds_dwordx4 v[228:229], off
	s_cmp_eq_u32 s72, 0
	s_cbranch_scc1 .Lw8_13
	s_waitcnt vmcnt(24)
	s_branch .Lwe_13

.Lwe_13:
	s_waitcnt lgkmcnt(0)
	s_barrier
	s_setprio 0
	s_waitcnt lgkmcnt(0)
	v_mfma_f32_16x16x32_bf16 v[62:65], v[158:161], v[190:193], v[62:65]
	v_mfma_f32_16x16x32_bf16 v[58:61], v[166:169], v[190:193], v[58:61]
	v_mfma_f32_16x16x32_bf16 v[54:57], v[158:161], v[198:201], v[54:57]
	v_mfma_f32_16x16x32_bf16 v[46:49], v[166:169], v[198:201], v[46:49]
	v_mfma_f32_16x16x32_bf16 v[38:41], v[158:161], v[206:209], v[38:41]
	v_mfma_f32_16x16x32_bf16 v[30:33], v[166:169], v[206:209], v[30:33]
	v_mfma_f32_16x16x32_bf16 v[22:25], v[158:161], v[214:217], v[22:25]
	v_mfma_f32_16x16x32_bf16 v[14:17], v[166:169], v[214:217], v[14:17]
	v_mfma_f32_16x16x32_bf16 v[62:65], v[162:165], v[194:197], v[62:65]
	v_mfma_f32_16x16x32_bf16 v[58:61], v[170:173], v[194:197], v[58:61]
	v_mfma_f32_16x16x32_bf16 v[54:57], v[162:165], v[202:205], v[54:57]
	v_mfma_f32_16x16x32_bf16 v[46:49], v[170:173], v[202:205], v[46:49]
	v_mfma_f32_16x16x32_bf16 v[38:41], v[162:165], v[210:213], v[38:41]
	v_mfma_f32_16x16x32_bf16 v[30:33], v[170:173], v[210:213], v[30:33]
	v_mfma_f32_16x16x32_bf16 v[22:25], v[162:165], v[218:221], v[22:25]
	v_mfma_f32_16x16x32_bf16 v[14:17], v[170:173], v[218:221], v[14:17]
	s_setprio 1
	s_setprio 0
	v_mfma_f32_16x16x32_bf16 v[50:53], v[174:177], v[190:193], v[50:53]
	v_mfma_f32_16x16x32_bf16 v[42:45], v[182:185], v[190:193], v[42:45]
	v_mfma_f32_16x16x32_bf16 v[34:37], v[174:177], v[198:201], v[34:37]
	v_mfma_f32_16x16x32_bf16 v[26:29], v[182:185], v[198:201], v[26:29]
	v_mfma_f32_16x16x32_bf16 v[18:21], v[174:177], v[206:209], v[18:21]
	v_mfma_f32_16x16x32_bf16 v[10:13], v[182:185], v[206:209], v[10:13]
	v_mfma_f32_16x16x32_bf16 v[6:9], v[174:177], v[214:217], v[6:9]
	v_mfma_f32_16x16x32_bf16 v[2:5], v[182:185], v[214:217], v[2:5]
	v_mfma_f32_16x16x32_bf16 v[50:53], v[178:181], v[194:197], v[50:53]
	v_mfma_f32_16x16x32_bf16 v[42:45], v[186:189], v[194:197], v[42:45]
	v_mfma_f32_16x16x32_bf16 v[34:37], v[178:181], v[202:205], v[34:37]
	v_mfma_f32_16x16x32_bf16 v[26:29], v[186:189], v[202:205], v[26:29]
	v_mfma_f32_16x16x32_bf16 v[18:21], v[178:181], v[210:213], v[18:21]
	v_mfma_f32_16x16x32_bf16 v[10:13], v[186:189], v[210:213], v[10:13]
	v_mfma_f32_16x16x32_bf16 v[6:9], v[178:181], v[218:221], v[6:9]
	v_mfma_f32_16x16x32_bf16 v[2:5], v[186:189], v[218:221], v[2:5]
	s_setprio 1
	s_barrier
	s_add_i32 s70, 0, 0x18000
	v_add_u32_e32 v157, s70, v150
	s_add_i32 s71, 0, 0x1c000
	ds_read_b128 v[158:161], v157
	ds_read_b128 v[162:165], v157 offset:1024
	ds_read_b128 v[166:169], v157 offset:2048
	ds_read_b128 v[170:173], v157 offset:3072
	v_add_u32_e32 v157, s71, v150
	ds_read_b128 v[174:177], v157
	ds_read_b128 v[178:181], v157 offset:1024
	ds_read_b128 v[182:185], v157 offset:2048
	ds_read_b128 v[186:189], v157 offset:3072
	s_add_u32 s42, s42, 0x80000
	s_addc_u32 s43, s43, 0
	s_mov_b32 m0, s53
	v_lshl_add_u64 v[230:231], s[42:43], 0, v[136:137]
	ds_read_b128 v[190:193], v156 offset:32768
	ds_read_b128 v[194:197], v156 offset:33792
	ds_read_b128 v[198:201], v156 offset:34816
	ds_read_b128 v[202:205], v156 offset:35840
	ds_read_b128 v[206:209], v156 offset:36864
	ds_read_b128 v[210:213], v156 offset:37888
	ds_read_b128 v[214:217], v156 offset:38912
	ds_read_b128 v[218:221], v156 offset:39936
	global_load_lds_dwordx4 v[230:231], off
	v_lshl_add_u64 v[230:231], s[42:43], 0, v[132:133]
	s_mov_b32 m0, s54
	s_nop 0
	global_load_lds_dwordx4 v[230:231], off
	s_waitcnt vmcnt(8)
	s_waitcnt lgkmcnt(0)
	s_barrier
	s_setprio 0
	s_waitcnt lgkmcnt(0)
	v_mfma_f32_16x16x32_bf16 v[126:129], v[158:161], v[190:193], v[126:129]
	v_mfma_f32_16x16x32_bf16 v[122:125], v[166:169], v[190:193], v[122:125]
	v_mfma_f32_16x16x32_bf16 v[118:121], v[158:161], v[198:201], v[118:121]
	v_mfma_f32_16x16x32_bf16 v[110:113], v[166:169], v[198:201], v[110:113]
	v_mfma_f32_16x16x32_bf16 v[102:105], v[158:161], v[206:209], v[102:105]
	v_mfma_f32_16x16x32_bf16 v[94:97], v[166:169], v[206:209], v[94:97]
	v_mfma_f32_16x16x32_bf16 v[86:89], v[158:161], v[214:217], v[86:89]
	v_mfma_f32_16x16x32_bf16 v[78:81], v[166:169], v[214:217], v[78:81]
	v_mfma_f32_16x16x32_bf16 v[126:129], v[162:165], v[194:197], v[126:129]
	v_mfma_f32_16x16x32_bf16 v[122:125], v[170:173], v[194:197], v[122:125]
	v_mfma_f32_16x16x32_bf16 v[118:121], v[162:165], v[202:205], v[118:121]
	v_mfma_f32_16x16x32_bf16 v[110:113], v[170:173], v[202:205], v[110:113]
	v_mfma_f32_16x16x32_bf16 v[102:105], v[162:165], v[210:213], v[102:105]
	v_mfma_f32_16x16x32_bf16 v[94:97], v[170:173], v[210:213], v[94:97]
	v_mfma_f32_16x16x32_bf16 v[86:89], v[162:165], v[218:221], v[86:89]
	v_mfma_f32_16x16x32_bf16 v[78:81], v[170:173], v[218:221], v[78:81]
	s_setprio 1
	s_setprio 0
	v_mfma_f32_16x16x32_bf16 v[114:117], v[174:177], v[190:193], v[114:117]
	v_mfma_f32_16x16x32_bf16 v[106:109], v[182:185], v[190:193], v[106:109]
	v_mfma_f32_16x16x32_bf16 v[98:101], v[174:177], v[198:201], v[98:101]
	v_mfma_f32_16x16x32_bf16 v[90:93], v[182:185], v[198:201], v[90:93]
	v_mfma_f32_16x16x32_bf16 v[82:85], v[174:177], v[206:209], v[82:85]
	v_mfma_f32_16x16x32_bf16 v[74:77], v[182:185], v[206:209], v[74:77]
	v_mfma_f32_16x16x32_bf16 v[70:73], v[174:177], v[214:217], v[70:73]
	v_mfma_f32_16x16x32_bf16 v[66:69], v[182:185], v[214:217], v[66:69]
	v_mfma_f32_16x16x32_bf16 v[114:117], v[178:181], v[194:197], v[114:117]
	v_mfma_f32_16x16x32_bf16 v[106:109], v[186:189], v[194:197], v[106:109]
	v_mfma_f32_16x16x32_bf16 v[98:101], v[178:181], v[202:205], v[98:101]
	v_mfma_f32_16x16x32_bf16 v[90:93], v[186:189], v[202:205], v[90:93]
	v_mfma_f32_16x16x32_bf16 v[82:85], v[178:181], v[210:213], v[82:85]
	v_mfma_f32_16x16x32_bf16 v[74:77], v[186:189], v[210:213], v[74:77]
	v_mfma_f32_16x16x32_bf16 v[70:73], v[178:181], v[218:221], v[70:73]
	v_mfma_f32_16x16x32_bf16 v[66:69], v[186:189], v[218:221], v[66:69]
	s_setprio 1
	s_barrier
	s_add_i32 s42, s70, s48
	v_lshl_add_u64 v[222:223], v[222:223], 0, s[12:13]
	s_mov_b32 m0, s42
	ds_read_b128 v[190:193], v156 offset:49152
	ds_read_b128 v[194:197], v156 offset:50176
	ds_read_b128 v[198:201], v156 offset:51200
	ds_read_b128 v[202:205], v156 offset:52224
	ds_read_b128 v[206:209], v156 offset:53248
	ds_read_b128 v[210:213], v156 offset:54272
	ds_read_b128 v[214:217], v156 offset:55296
	ds_read_b128 v[218:221], v156 offset:56320
	global_load_lds_dwordx4 v[222:223], off
	s_add_i32 m0, s42, 0x2000
	s_add_u32 s40, s40, 0x80080
	v_lshl_add_u64 v[222:223], v[224:225], 0, s[12:13]
	s_addc_u32 s41, s41, 0
	s_add_i32 s42, s71, s48
	global_load_lds_dwordx4 v[222:223], off
	v_lshl_add_u64 v[222:223], s[40:41], 0, v[134:135]
	s_mov_b32 m0, s42
	s_nop 0
	global_load_lds_dwordx4 v[222:223], off
	v_lshl_add_u64 v[222:223], s[40:41], 0, v[130:131]
	s_add_i32 m0, s42, 0x2000
	s_nop 0
	global_load_lds_dwordx4 v[222:223], off
	v_lshl_add_u64 v[222:223], v[226:227], 0, s[12:13]
	s_mov_b32 m0, s56
	s_nop 0
	global_load_lds_dwordx4 v[222:223], off
	v_lshl_add_u64 v[222:223], v[228:229], 0, s[12:13]
	s_mov_b32 m0, s57
	s_nop 0
	global_load_lds_dwordx4 v[222:223], off
	s_waitcnt vmcnt(8)
	s_waitcnt lgkmcnt(0)
	s_barrier
	s_setprio 0
	s_waitcnt lgkmcnt(0)
	v_mfma_f32_16x16x32_bf16 v[62:65], v[158:161], v[190:193], v[62:65]
	v_mfma_f32_16x16x32_bf16 v[58:61], v[166:169], v[190:193], v[58:61]
	v_mfma_f32_16x16x32_bf16 v[54:57], v[158:161], v[198:201], v[54:57]
	v_mfma_f32_16x16x32_bf16 v[46:49], v[166:169], v[198:201], v[46:49]
	v_mfma_f32_16x16x32_bf16 v[38:41], v[158:161], v[206:209], v[38:41]
	v_mfma_f32_16x16x32_bf16 v[30:33], v[166:169], v[206:209], v[30:33]
	v_mfma_f32_16x16x32_bf16 v[22:25], v[158:161], v[214:217], v[22:25]
	v_mfma_f32_16x16x32_bf16 v[14:17], v[166:169], v[214:217], v[14:17]
	v_mfma_f32_16x16x32_bf16 v[62:65], v[162:165], v[194:197], v[62:65]
	v_mfma_f32_16x16x32_bf16 v[58:61], v[170:173], v[194:197], v[58:61]
	v_mfma_f32_16x16x32_bf16 v[54:57], v[162:165], v[202:205], v[54:57]
	v_mfma_f32_16x16x32_bf16 v[46:49], v[170:173], v[202:205], v[46:49]
	v_mfma_f32_16x16x32_bf16 v[38:41], v[162:165], v[210:213], v[38:41]
	v_mfma_f32_16x16x32_bf16 v[30:33], v[170:173], v[210:213], v[30:33]
	v_mfma_f32_16x16x32_bf16 v[22:25], v[162:165], v[218:221], v[22:25]
	v_mfma_f32_16x16x32_bf16 v[14:17], v[170:173], v[218:221], v[14:17]
	s_setprio 1
	s_setprio 0
	v_mfma_f32_16x16x32_bf16 v[50:53], v[174:177], v[190:193], v[50:53]
	v_mfma_f32_16x16x32_bf16 v[42:45], v[182:185], v[190:193], v[42:45]
	v_mfma_f32_16x16x32_bf16 v[34:37], v[174:177], v[198:201], v[34:37]
	v_mfma_f32_16x16x32_bf16 v[26:29], v[182:185], v[198:201], v[26:29]
	v_mfma_f32_16x16x32_bf16 v[18:21], v[174:177], v[206:209], v[18:21]
	v_mfma_f32_16x16x32_bf16 v[10:13], v[182:185], v[206:209], v[10:13]
	v_mfma_f32_16x16x32_bf16 v[6:9], v[174:177], v[214:217], v[6:9]
	v_mfma_f32_16x16x32_bf16 v[2:5], v[182:185], v[214:217], v[2:5]
	v_mfma_f32_16x16x32_bf16 v[50:53], v[178:181], v[194:197], v[50:53]
	v_mfma_f32_16x16x32_bf16 v[42:45], v[186:189], v[194:197], v[42:45]
	v_mfma_f32_16x16x32_bf16 v[34:37], v[178:181], v[202:205], v[34:37]
	v_mfma_f32_16x16x32_bf16 v[26:29], v[186:189], v[202:205], v[26:29]
	v_mfma_f32_16x16x32_bf16 v[18:21], v[178:181], v[210:213], v[18:21]
	v_mfma_f32_16x16x32_bf16 v[10:13], v[186:189], v[210:213], v[10:13]
	v_mfma_f32_16x16x32_bf16 v[6:9], v[178:181], v[218:221], v[6:9]
	v_mfma_f32_16x16x32_bf16 v[2:5], v[186:189], v[218:221], v[2:5]
	s_setprio 1
	s_barrier
	s_add_i32 s69, s69, 2
	s_add_u32 s38, s38, 0x100
	s_addc_u32 s39, s39, 0
	s_cmp_gt_u32 s69, 29
	s_cbranch_scc0 .LBB0_1587
	s_and_b64 vcc, exec, s[14:15]
	s_cbranch_vccnz .LBB0_1592
	s_mov_b64 s[30:31], -1
	s_and_b64 vcc, exec, s[34:35]
	s_cbranch_vccnz .LBB0_1593
